# equal wave priority in the attention loops: the 64 s_setprio around the QK/PV MFMA clusters replaced by s_nop 0
# speedup vs baseline: 1.0005x; 1.0005x over previous
.LBB0_162:
	ds_read_b128 v[32:35], v115
	ds_read_b128 v[98:101], v115 offset:32
	ds_read_b128 v[36:39], v115 offset:4608
	ds_read_b128 v[102:105], v115 offset:4640
	ds_read_b128 v[106:109], v115 offset:64
	ds_read_b128 v[110:113], v115 offset:96
	ds_read_b128 v[122:125], v115 offset:4672
	ds_read_b128 v[126:129], v115 offset:4704
	s_nop 0
	s_nop 0
	s_waitcnt lgkmcnt(7)
	v_mfma_f32_32x32x16_bf16 v[48:63], v[32:35], v[64:67], 0
	s_waitcnt lgkmcnt(5)
	v_mfma_f32_32x32x16_bf16 v[32:47], v[36:39], v[64:67], 0
	v_mfma_f32_32x32x16_bf16 v[48:63], v[98:101], v[68:71], v[48:63]
	s_waitcnt lgkmcnt(4)
	v_mfma_f32_32x32x16_bf16 v[32:47], v[102:105], v[68:71], v[32:47]
	s_waitcnt lgkmcnt(3)
	v_mfma_f32_32x32x16_bf16 v[48:63], v[106:109], v[72:75], v[48:63]
	s_waitcnt lgkmcnt(1)
	v_mfma_f32_32x32x16_bf16 v[32:47], v[122:125], v[72:75], v[32:47]
	v_mfma_f32_32x32x16_bf16 v[48:63], v[110:113], v[76:79], v[48:63]
	ds_read_b128 v[110:113], v119 offset:9216
	ds_read_b128 v[106:109], v119 offset:9248
	ds_read_b128 v[102:105], v119 offset:9280
	ds_read_b128 v[98:101], v119 offset:9312
	s_waitcnt lgkmcnt(4)
	v_mfma_f32_32x32x16_bf16 v[32:47], v[126:129], v[76:79], v[32:47]
	s_nop 11
	v_max3_f32 v96, v32, v33, v34
	v_max3_f32 v96, v96, v35, v36
	v_max3_f32 v96, v96, v37, v38
	v_max3_f32 v96, v96, v39, v40
	v_max3_f32 v96, v96, v41, v42
	v_max3_f32 v96, v96, v43, v44
	v_max3_f32 v96, v96, v45, v46
	v_max3_f32 v96, v96, v47, v48
	v_max3_f32 v96, v96, v49, v50
	v_max3_f32 v96, v96, v51, v52
	v_max3_f32 v96, v96, v53, v54
	v_max3_f32 v96, v96, v55, v56
	v_max3_f32 v96, v96, v57, v58
	v_max3_f32 v96, v96, v59, v60
	v_max3_f32 v96, v96, v61, v62
	v_max_f32_e32 v96, v96, v63
	v_mov_b32_e32 v122, v96
	s_nop 1
	v_permlane32_swap_b32_e32 v96, v122
	v_max3_f32 v122, v120, v96, v122
	v_add_f32_e32 v96, 0x41000000, v120
	v_cmp_gt_f32_e32 vcc, v122, v96
	s_cbranch_vccz .LBB0_164
	v_sub_f32_e32 v96, v120, v122
	v_exp_f32_e32 v96, v96
	s_nop 0
	v_mul_f32_e32 v121, v121, v96
	v_pk_mul_f32 v[14:15], v[14:15], v[96:97] op_sel_hi:[1,0]
	v_pk_mul_f32 v[12:13], v[12:13], v[96:97] op_sel_hi:[1,0]
	v_pk_mul_f32 v[10:11], v[10:11], v[96:97] op_sel_hi:[1,0]
	v_pk_mul_f32 v[8:9], v[8:9], v[96:97] op_sel_hi:[1,0]
	v_pk_mul_f32 v[6:7], v[6:7], v[96:97] op_sel_hi:[1,0]
	v_pk_mul_f32 v[4:5], v[4:5], v[96:97] op_sel_hi:[1,0]
	v_pk_mul_f32 v[2:3], v[2:3], v[96:97] op_sel_hi:[1,0]
	v_pk_mul_f32 v[0:1], v[0:1], v[96:97] op_sel_hi:[1,0]
	v_pk_mul_f32 v[30:31], v[30:31], v[96:97] op_sel_hi:[1,0]
	v_pk_mul_f32 v[28:29], v[28:29], v[96:97] op_sel_hi:[1,0]
	v_pk_mul_f32 v[26:27], v[26:27], v[96:97] op_sel_hi:[1,0]
	v_pk_mul_f32 v[24:25], v[24:25], v[96:97] op_sel_hi:[1,0]
	v_pk_mul_f32 v[22:23], v[22:23], v[96:97] op_sel_hi:[1,0]
	v_pk_mul_f32 v[20:21], v[20:21], v[96:97] op_sel_hi:[1,0]
	v_pk_mul_f32 v[18:19], v[18:19], v[96:97] op_sel_hi:[1,0]
	v_pk_mul_f32 v[16:17], v[16:17], v[96:97] op_sel_hi:[1,0]
	s_branch .LBB0_165

.LBB0_165:
	ds_read_b128 v[136:139], v119 offset:13824
	ds_read_b128 v[140:143], v119 offset:13856
	ds_read_b128 v[144:147], v119 offset:13888
	ds_read_b128 v[148:151], v119 offset:13920
	v_sub_f32_e32 v48, v48, v122
	v_sub_f32_e32 v32, v32, v122
	v_sub_f32_e32 v49, v49, v122
	v_sub_f32_e32 v33, v33, v122
	v_sub_f32_e32 v50, v50, v122
	v_sub_f32_e32 v34, v34, v122
	v_sub_f32_e32 v51, v51, v122
	v_sub_f32_e32 v35, v35, v122
	v_sub_f32_e32 v52, v52, v122
	v_sub_f32_e32 v36, v36, v122
	v_sub_f32_e32 v53, v53, v122
	v_sub_f32_e32 v37, v37, v122
	v_sub_f32_e32 v54, v54, v122
	v_sub_f32_e32 v38, v38, v122
	v_sub_f32_e32 v55, v55, v122
	v_sub_f32_e32 v39, v39, v122
	v_sub_f32_e32 v56, v56, v122
	v_sub_f32_e32 v40, v40, v122
	v_sub_f32_e32 v57, v57, v122
	v_sub_f32_e32 v41, v41, v122
	v_sub_f32_e32 v58, v58, v122
	v_sub_f32_e32 v42, v42, v122
	v_sub_f32_e32 v59, v59, v122
	v_sub_f32_e32 v43, v43, v122
	v_sub_f32_e32 v60, v60, v122
	v_sub_f32_e32 v44, v44, v122
	v_sub_f32_e32 v61, v61, v122
	v_sub_f32_e32 v45, v45, v122
	v_sub_f32_e32 v62, v62, v122
	v_sub_f32_e32 v46, v46, v122
	v_sub_f32_e32 v63, v63, v122
	v_sub_f32_e32 v47, v47, v122
	v_exp_f32_e32 v48, v48
	v_exp_f32_e32 v32, v32
	v_exp_f32_e32 v49, v49
	v_exp_f32_e32 v33, v33
	v_exp_f32_e32 v50, v50
	v_exp_f32_e32 v34, v34
	v_exp_f32_e32 v51, v51
	v_exp_f32_e32 v35, v35
	v_exp_f32_e32 v52, v52
	v_exp_f32_e32 v36, v36
	v_exp_f32_e32 v53, v53
	v_exp_f32_e32 v37, v37
	v_exp_f32_e32 v54, v54
	v_exp_f32_e32 v38, v38
	v_exp_f32_e32 v55, v55
	v_exp_f32_e32 v39, v39
	v_exp_f32_e32 v56, v56
	v_exp_f32_e32 v40, v40
	v_exp_f32_e32 v57, v57
	v_exp_f32_e32 v41, v41
	v_exp_f32_e32 v58, v58
	v_exp_f32_e32 v42, v42
	v_exp_f32_e32 v59, v59
	v_exp_f32_e32 v43, v43
	v_exp_f32_e32 v60, v60
	v_exp_f32_e32 v44, v44
	v_exp_f32_e32 v61, v61
	v_exp_f32_e32 v45, v45
	v_exp_f32_e32 v62, v62
	v_exp_f32_e32 v46, v46
	v_exp_f32_e32 v63, v63
	v_exp_f32_e32 v47, v47
	v_cvt_pk_bf16_f32 v124, v48, v49
	v_cvt_pk_bf16_f32 v125, v50, v51
	v_cvt_pk_bf16_f32 v126, v52, v53
	v_cvt_pk_bf16_f32 v127, v54, v55
	v_cvt_pk_bf16_f32 v128, v32, v33
	v_cvt_pk_bf16_f32 v129, v34, v35
	v_cvt_pk_bf16_f32 v130, v36, v37
	v_cvt_pk_bf16_f32 v131, v38, v39
	v_cvt_pk_bf16_f32 v132, v56, v57
	v_cvt_pk_bf16_f32 v133, v58, v59
	v_cvt_pk_bf16_f32 v134, v60, v61
	v_cvt_pk_bf16_f32 v135, v62, v63
	v_cvt_pk_bf16_f32 v152, v40, v41
	v_cvt_pk_bf16_f32 v153, v42, v43
	v_cvt_pk_bf16_f32 v154, v44, v45
	v_cvt_pk_bf16_f32 v155, v46, v47
	s_nop 0
	s_waitcnt lgkmcnt(7)
	v_mfma_f32_32x32x16_bf16 v[16:31], v[110:113], v[124:127], v[16:31]
	s_waitcnt lgkmcnt(6)
	v_mfma_f32_32x32x16_bf16 v[16:31], v[106:109], v[132:135], v[16:31]
	s_waitcnt lgkmcnt(5)
	v_mfma_f32_32x32x16_bf16 v[16:31], v[102:105], v[128:131], v[16:31]
	s_waitcnt lgkmcnt(4)
	v_mfma_f32_32x32x16_bf16 v[16:31], v[98:101], v[152:155], v[16:31]
	s_nop 0
	s_nop 0
	s_waitcnt lgkmcnt(3)
	v_mfma_f32_32x32x16_bf16 v[0:15], v[136:139], v[124:127], v[0:15]
	s_waitcnt lgkmcnt(2)
	v_mfma_f32_32x32x16_bf16 v[0:15], v[140:143], v[132:135], v[0:15]
	s_waitcnt lgkmcnt(1)
	v_mfma_f32_32x32x16_bf16 v[0:15], v[144:147], v[128:131], v[0:15]
	s_waitcnt lgkmcnt(0)
	v_mfma_f32_32x32x16_bf16 v[0:15], v[148:151], v[152:155], v[0:15]
	s_nop 0
	v_mov_b32_e32 v96, v204
	s_andn2_b64 vcc, exec, s[50:51]
	v_lshrrev_b32_e32 v98, 3, v96
	v_lshlrev_b32_e32 v96, 4, v96
	v_mul_lo_u32 v98, v98, s55
	v_and_b32_e32 v96, 0x70, v96
	v_add3_u32 v96, 0, v98, v96
	s_waitcnt vmcnt(1)
	ds_write_b128 v96, v[80:83] offset:18432
	s_waitcnt vmcnt(0)
	ds_write_b128 v96, v[84:87] offset:27648
	v_cndmask_b32_e64 v96, 0, 1, s[50:51]
	v_cmp_ne_u32_e64 s[0:1], 1, v96
	s_waitcnt lgkmcnt(0)
	s_barrier
	s_cbranch_vccnz .LBB0_167
	v_mov_b32_e32 v84, v204
	s_nop 0
	v_ashrrev_i32_e32 v80, 3, v84
	v_ashrrev_i32_e32 v81, 31, v80
	v_lshlrev_b64 v[82:83], 7, v[80:81]
	v_lshlrev_b32_e32 v84, 4, v84
	v_lshl_add_u64 v[82:83], s[40:41], 0, v[82:83]
	v_and_b32_e32 v96, 0x70, v84
	v_lshl_add_u64 v[82:83], v[82:83], 0, v[96:97]
	v_lshlrev_b64 v[80:81], 9, v[80:81]
	v_add_co_u32_e32 v82, vcc, 0x6000, v82
	v_lshl_add_u64 v[80:81], s[48:49], 0, v[80:81]
	s_nop 0
	v_addc_co_u32_e32 v83, vcc, 0, v83, vcc
	v_lshl_add_u64 v[84:85], v[80:81], 0, v[96:97]
	global_load_dwordx4 v[80:83], v[82:83], off
	s_nop 0
	global_load_dwordx4 v[84:87], v[84:85], off offset:384
.LBB0_167:
	v_add_f32_e32 v32, v48, v32
	v_add_f32_e32 v32, 0, v32
	v_add_f32_e32 v33, v49, v33
	v_add_f32_e32 v32, v33, v32
	v_add_f32_e32 v33, v50, v34
	v_add_f32_e32 v32, v33, v32
	v_add_f32_e32 v33, v51, v35
	v_add_f32_e32 v32, v33, v32
	v_add_f32_e32 v33, v52, v36
	v_add_f32_e32 v32, v33, v32
	v_add_f32_e32 v33, v53, v37
	v_add_f32_e32 v32, v33, v32
	v_add_f32_e32 v33, v54, v38
	v_add_f32_e32 v32, v33, v32
	v_add_f32_e32 v33, v55, v39
	v_add_f32_e32 v32, v33, v32
	v_add_f32_e32 v33, v56, v40
	v_add_f32_e32 v32, v33, v32
	v_add_f32_e32 v33, v57, v41
	v_add_f32_e32 v32, v33, v32
	v_add_f32_e32 v33, v58, v42
	v_add_f32_e32 v32, v33, v32
	v_add_f32_e32 v33, v59, v43
	v_add_f32_e32 v32, v33, v32
	v_add_f32_e32 v33, v60, v44
	v_add_f32_e32 v32, v33, v32
	v_add_f32_e32 v33, v61, v45
	v_add_f32_e32 v32, v33, v32
	v_add_f32_e32 v33, v62, v46
	v_add_f32_e32 v32, v33, v32
	v_add_f32_e32 v33, v63, v47
	v_add_f32_e32 v32, v33, v32
	v_add_f32_e32 v96, v121, v32
	ds_read_b128 v[32:35], v115 offset:23040
	ds_read_b128 v[36:39], v115 offset:18432
	ds_read_b128 v[98:101], v115 offset:18464
	ds_read_b128 v[102:105], v115 offset:23072
	ds_read_b128 v[106:109], v115 offset:18496
	ds_read_b128 v[110:113], v115 offset:23104
	ds_read_b128 v[124:127], v115 offset:18528
	ds_read_b128 v[128:131], v115 offset:23136
	s_nop 0
	s_nop 0
	s_waitcnt lgkmcnt(6)
	v_mfma_f32_32x32x16_bf16 v[48:63], v[36:39], v[64:67], 0
	v_mfma_f32_32x32x16_bf16 v[32:47], v[32:35], v[64:67], 0
	s_waitcnt lgkmcnt(5)
	v_mfma_f32_32x32x16_bf16 v[48:63], v[98:101], v[68:71], v[48:63]
	s_waitcnt lgkmcnt(4)
	v_mfma_f32_32x32x16_bf16 v[32:47], v[102:105], v[68:71], v[32:47]
	s_waitcnt lgkmcnt(3)
	v_mfma_f32_32x32x16_bf16 v[48:63], v[106:109], v[72:75], v[48:63]
	s_waitcnt lgkmcnt(2)
	v_mfma_f32_32x32x16_bf16 v[32:47], v[110:113], v[72:75], v[32:47]
	ds_read_b128 v[110:113], v119 offset:27648
	ds_read_b128 v[106:109], v119 offset:27680
	ds_read_b128 v[102:105], v119 offset:27712
	ds_read_b128 v[98:101], v119 offset:27744
	s_waitcnt lgkmcnt(5)
	v_mfma_f32_32x32x16_bf16 v[48:63], v[124:127], v[76:79], v[48:63]
	s_waitcnt lgkmcnt(4)
	v_mfma_f32_32x32x16_bf16 v[32:47], v[128:131], v[76:79], v[32:47]
	s_nop 11
	v_max3_f32 v120, v32, v33, v34
	v_max3_f32 v120, v120, v35, v36
	v_max3_f32 v120, v120, v37, v38
	v_max3_f32 v120, v120, v39, v40
	v_max3_f32 v120, v120, v41, v42
	v_max3_f32 v120, v120, v43, v44
	v_max3_f32 v120, v120, v45, v46
	v_max3_f32 v120, v120, v47, v48
	v_max3_f32 v120, v120, v49, v50
	v_max3_f32 v120, v120, v51, v52
	v_max3_f32 v120, v120, v53, v54
	v_max3_f32 v120, v120, v55, v56
	v_max3_f32 v120, v120, v57, v58
	v_max3_f32 v120, v120, v59, v60
	v_max3_f32 v120, v120, v61, v62
	v_max_f32_e32 v120, v120, v63
	v_mov_b32_e32 v121, v120
	s_nop 1
	v_permlane32_swap_b32_e32 v120, v121
	v_max3_f32 v120, v122, v120, v121
	v_add_f32_e32 v121, 0x41000000, v122
	v_cmp_gt_f32_e32 vcc, v120, v121
	s_cbranch_vccz .LBB0_169
	v_sub_f32_e32 v121, v122, v120
	v_exp_f32_e32 v122, v121
	s_nop 0
	v_mul_f32_e32 v96, v96, v122
	v_pk_mul_f32 v[14:15], v[14:15], v[122:123] op_sel_hi:[1,0]
	v_pk_mul_f32 v[12:13], v[12:13], v[122:123] op_sel_hi:[1,0]
	v_pk_mul_f32 v[10:11], v[10:11], v[122:123] op_sel_hi:[1,0]
	v_pk_mul_f32 v[8:9], v[8:9], v[122:123] op_sel_hi:[1,0]
	v_pk_mul_f32 v[6:7], v[6:7], v[122:123] op_sel_hi:[1,0]
	v_pk_mul_f32 v[4:5], v[4:5], v[122:123] op_sel_hi:[1,0]
	v_pk_mul_f32 v[2:3], v[2:3], v[122:123] op_sel_hi:[1,0]
	v_pk_mul_f32 v[0:1], v[0:1], v[122:123] op_sel_hi:[1,0]
	v_pk_mul_f32 v[30:31], v[30:31], v[122:123] op_sel_hi:[1,0]
	v_pk_mul_f32 v[28:29], v[28:29], v[122:123] op_sel_hi:[1,0]
	v_pk_mul_f32 v[26:27], v[26:27], v[122:123] op_sel_hi:[1,0]
	v_pk_mul_f32 v[24:25], v[24:25], v[122:123] op_sel_hi:[1,0]
	v_pk_mul_f32 v[22:23], v[22:23], v[122:123] op_sel_hi:[1,0]
	v_pk_mul_f32 v[20:21], v[20:21], v[122:123] op_sel_hi:[1,0]
	v_pk_mul_f32 v[18:19], v[18:19], v[122:123] op_sel_hi:[1,0]
	v_pk_mul_f32 v[16:17], v[16:17], v[122:123] op_sel_hi:[1,0]
	s_branch .LBB0_170

.LBB0_170:
	ds_read_b128 v[134:137], v119 offset:32256
	ds_read_b128 v[138:141], v119 offset:32288
	ds_read_b128 v[142:145], v119 offset:32320
	ds_read_b128 v[146:149], v119 offset:32352
	v_sub_f32_e32 v48, v48, v120
	v_sub_f32_e32 v32, v32, v120
	v_sub_f32_e32 v49, v49, v120
	v_sub_f32_e32 v33, v33, v120
	v_sub_f32_e32 v50, v50, v120
	v_sub_f32_e32 v34, v34, v120
	v_sub_f32_e32 v51, v51, v120
	v_sub_f32_e32 v35, v35, v120
	v_sub_f32_e32 v52, v52, v120
	v_sub_f32_e32 v36, v36, v120
	v_sub_f32_e32 v53, v53, v120
	v_sub_f32_e32 v37, v37, v120
	v_sub_f32_e32 v54, v54, v120
	v_sub_f32_e32 v38, v38, v120
	v_sub_f32_e32 v55, v55, v120
	v_sub_f32_e32 v39, v39, v120
	v_sub_f32_e32 v56, v56, v120
	v_sub_f32_e32 v40, v40, v120
	v_sub_f32_e32 v57, v57, v120
	v_sub_f32_e32 v41, v41, v120
	v_sub_f32_e32 v58, v58, v120
	v_sub_f32_e32 v42, v42, v120
	v_sub_f32_e32 v59, v59, v120
	v_sub_f32_e32 v43, v43, v120
	v_sub_f32_e32 v60, v60, v120
	v_sub_f32_e32 v44, v44, v120
	v_sub_f32_e32 v61, v61, v120
	v_sub_f32_e32 v45, v45, v120
	v_sub_f32_e32 v62, v62, v120
	v_sub_f32_e32 v46, v46, v120
	v_sub_f32_e32 v63, v63, v120
	v_sub_f32_e32 v47, v47, v120
	v_exp_f32_e32 v48, v48
	v_exp_f32_e32 v32, v32
	v_exp_f32_e32 v49, v49
	v_exp_f32_e32 v33, v33
	v_exp_f32_e32 v50, v50
	v_exp_f32_e32 v34, v34
	v_exp_f32_e32 v51, v51
	v_exp_f32_e32 v35, v35
	v_exp_f32_e32 v52, v52
	v_exp_f32_e32 v36, v36
	v_exp_f32_e32 v53, v53
	v_exp_f32_e32 v37, v37
	v_exp_f32_e32 v54, v54
	v_exp_f32_e32 v38, v38
	v_exp_f32_e32 v55, v55
	v_exp_f32_e32 v39, v39
	v_exp_f32_e32 v56, v56
	v_exp_f32_e32 v40, v40
	v_exp_f32_e32 v57, v57
	v_exp_f32_e32 v41, v41
	v_exp_f32_e32 v58, v58
	v_exp_f32_e32 v42, v42
	v_exp_f32_e32 v59, v59
	v_exp_f32_e32 v43, v43
	v_exp_f32_e32 v60, v60
	v_exp_f32_e32 v44, v44
	v_exp_f32_e32 v61, v61
	v_exp_f32_e32 v45, v45
	v_exp_f32_e32 v62, v62
	v_exp_f32_e32 v46, v46
	v_exp_f32_e32 v63, v63
	v_exp_f32_e32 v47, v47
	v_cvt_pk_bf16_f32 v122, v48, v49
	v_cvt_pk_bf16_f32 v123, v50, v51
	v_cvt_pk_bf16_f32 v124, v52, v53
	v_cvt_pk_bf16_f32 v125, v54, v55
	v_cvt_pk_bf16_f32 v126, v32, v33
	v_cvt_pk_bf16_f32 v127, v34, v35
	v_cvt_pk_bf16_f32 v128, v36, v37
	v_cvt_pk_bf16_f32 v129, v38, v39
	v_cvt_pk_bf16_f32 v130, v56, v57
	v_cvt_pk_bf16_f32 v131, v58, v59
	v_cvt_pk_bf16_f32 v132, v60, v61
	v_cvt_pk_bf16_f32 v133, v62, v63
	v_cvt_pk_bf16_f32 v150, v40, v41
	v_cvt_pk_bf16_f32 v151, v42, v43
	v_cvt_pk_bf16_f32 v152, v44, v45
	v_cvt_pk_bf16_f32 v153, v46, v47
	s_nop 0
	s_waitcnt lgkmcnt(7)
	v_mfma_f32_32x32x16_bf16 v[16:31], v[110:113], v[122:125], v[16:31]
	s_waitcnt lgkmcnt(6)
	v_mfma_f32_32x32x16_bf16 v[16:31], v[106:109], v[130:133], v[16:31]
	s_waitcnt lgkmcnt(5)
	v_mfma_f32_32x32x16_bf16 v[16:31], v[102:105], v[126:129], v[16:31]
	s_waitcnt lgkmcnt(4)
	v_mfma_f32_32x32x16_bf16 v[16:31], v[98:101], v[150:153], v[16:31]
	s_nop 0
	s_nop 0
	s_waitcnt lgkmcnt(3)
	v_mfma_f32_32x32x16_bf16 v[0:15], v[134:137], v[122:125], v[0:15]
	s_waitcnt lgkmcnt(2)
	v_mfma_f32_32x32x16_bf16 v[0:15], v[138:141], v[130:133], v[0:15]
	s_waitcnt lgkmcnt(1)
	v_mfma_f32_32x32x16_bf16 v[0:15], v[142:145], v[126:129], v[0:15]
	s_waitcnt lgkmcnt(0)
	v_mfma_f32_32x32x16_bf16 v[0:15], v[146:149], v[150:153], v[0:15]
	s_nop 0
	s_and_b64 vcc, exec, s[0:1]
	s_cbranch_vccnz .LBB0_161
	v_mov_b32_e32 v98, v204
	s_nop 0
	v_lshrrev_b32_e32 v99, 3, v98
	v_lshlrev_b32_e32 v98, 4, v98
	v_mul_lo_u32 v99, v99, s55
	v_and_b32_e32 v98, 0x70, v98
	v_add3_u32 v98, 0, v99, v98
	s_waitcnt vmcnt(1)
	ds_write_b128 v98, v[88:91]
	s_waitcnt vmcnt(0)
	ds_write_b128 v98, v[92:95] offset:9216
	s_branch .LBB0_161

.LBB0_185:
	v_cndmask_b32_e64 v32, 0, 1, s[40:41]
	v_cmp_ne_u32_e64 s[0:1], 1, v32
	s_and_saveexec_b64 s[40:41], s[68:69]
	s_cbranch_execz .LBB0_192
	v_add_u32_e32 v40, v122, v116
	ds_read_b128 v[32:35], v40
	ds_read_b128 v[98:101], v40 offset:32
	ds_read_b128 v[36:39], v40 offset:4608
	ds_read_b128 v[102:105], v40 offset:4640
	ds_read_b128 v[106:109], v40 offset:64
	ds_read_b128 v[110:113], v40 offset:96
	ds_read_b128 v[126:129], v40 offset:4672
	ds_read_b128 v[130:133], v40 offset:4704
	s_nop 0
	s_nop 0
	s_waitcnt lgkmcnt(7)
	v_mfma_f32_32x32x16_bf16 v[48:63], v[32:35], v[64:67], 0
	s_waitcnt lgkmcnt(5)
	v_mfma_f32_32x32x16_bf16 v[32:47], v[36:39], v[64:67], 0
	v_mfma_f32_32x32x16_bf16 v[48:63], v[98:101], v[68:71], v[48:63]
	s_waitcnt lgkmcnt(4)
	v_mfma_f32_32x32x16_bf16 v[32:47], v[102:105], v[68:71], v[32:47]
	s_waitcnt lgkmcnt(3)
	v_mfma_f32_32x32x16_bf16 v[48:63], v[106:109], v[72:75], v[48:63]
	s_waitcnt lgkmcnt(1)
	v_mfma_f32_32x32x16_bf16 v[32:47], v[126:129], v[72:75], v[32:47]
	v_add_u32_e32 v126, v123, v116
	v_mfma_f32_32x32x16_bf16 v[48:63], v[110:113], v[76:79], v[48:63]
	ds_read_b128 v[110:113], v126 offset:9216
	ds_read_b128 v[106:109], v126 offset:9248
	ds_read_b128 v[102:105], v126 offset:9280
	ds_read_b128 v[98:101], v126 offset:9312
	s_waitcnt lgkmcnt(4)
	v_mfma_f32_32x32x16_bf16 v[32:47], v[130:133], v[76:79], v[32:47]
	s_and_b64 vcc, exec, s[0:1]
	s_cbranch_vccnz .LBB0_188
	s_add_i32 s10, s27, -1
	v_add_u32_e32 v156, s10, v124
	s_lshl_b32 s11, s27, 1
	s_add_i32 s11, s11, -1
	v_add_u32_e32 v96, 0x77, v156
	v_add_u32_e32 v127, 0x57, v156
	v_add_u32_e32 v128, 0x76, v156
	v_cmp_gt_u32_e64 s[4:5], s11, v96
	v_cmp_gt_u32_e64 s[6:7], s11, v127
	v_cmp_gt_u32_e64 s[8:9], s11, v128
	v_cndmask_b32_e64 v48, v212, v48, s[4:5]
	v_cndmask_b32_e64 v32, v212, v32, s[6:7]
	v_cndmask_b32_e64 v49, v212, v49, s[8:9]
	v_add_u32_e32 v96, 0x56, v156
	v_add_u32_e32 v127, 0x75, v156
	v_add_u32_e32 v128, 0x55, v156
	v_cmp_gt_u32_e64 s[4:5], s11, v96
	v_cmp_gt_u32_e64 s[6:7], s11, v127
	v_cmp_gt_u32_e64 s[8:9], s11, v128
	v_cndmask_b32_e64 v33, v212, v33, s[4:5]
	v_cndmask_b32_e64 v50, v212, v50, s[6:7]
	v_cndmask_b32_e64 v34, v212, v34, s[8:9]
	v_add_u32_e32 v96, 0x74, v156
	v_add_u32_e32 v127, 0x54, v156
	v_add_u32_e32 v128, 0x73, v156
	v_cmp_gt_u32_e64 s[4:5], s11, v96
	v_cmp_gt_u32_e64 s[6:7], s11, v127
	v_cmp_gt_u32_e64 s[8:9], s11, v128
	v_cndmask_b32_e64 v51, v212, v51, s[4:5]
	v_cndmask_b32_e64 v35, v212, v35, s[6:7]
	v_cndmask_b32_e64 v52, v212, v52, s[8:9]
	v_add_u32_e32 v96, 0x53, v156
	v_add_u32_e32 v127, 0x72, v156
	v_add_u32_e32 v128, 0x52, v156
	v_cmp_gt_u32_e64 s[4:5], s11, v96
	v_cmp_gt_u32_e64 s[6:7], s11, v127
	v_cmp_gt_u32_e64 s[8:9], s11, v128
	v_cndmask_b32_e64 v36, v212, v36, s[4:5]
	v_cndmask_b32_e64 v53, v212, v53, s[6:7]
	v_cndmask_b32_e64 v37, v212, v37, s[8:9]
	v_add_u32_e32 v96, 0x71, v156
	v_add_u32_e32 v127, 0x51, v156
	v_add_u32_e32 v128, 0x70, v156
	v_cmp_gt_u32_e64 s[4:5], s11, v96
	v_cmp_gt_u32_e64 s[6:7], s11, v127
	v_cmp_gt_u32_e64 s[8:9], s11, v128
	v_cndmask_b32_e64 v54, v212, v54, s[4:5]
	v_cndmask_b32_e64 v38, v212, v38, s[6:7]
	v_cndmask_b32_e64 v55, v212, v55, s[8:9]
	v_add_u32_e32 v96, 0x50, v156
	v_add_u32_e32 v127, 0x67, v156
	v_add_u32_e32 v128, 0x47, v156
	v_cmp_gt_u32_e64 s[4:5], s11, v96
	v_cmp_gt_u32_e64 s[6:7], s11, v127
	v_cmp_gt_u32_e64 s[8:9], s11, v128
	v_cndmask_b32_e64 v39, v212, v39, s[4:5]
	v_cndmask_b32_e64 v56, v212, v56, s[6:7]
	v_cndmask_b32_e64 v40, v212, v40, s[8:9]
	v_add_u32_e32 v96, 0x66, v156
	v_add_u32_e32 v127, 0x46, v156
	v_add_u32_e32 v128, 0x65, v156
	v_cmp_gt_u32_e64 s[4:5], s11, v96
	v_cmp_gt_u32_e64 s[6:7], s11, v127
	v_cmp_gt_u32_e64 s[8:9], s11, v128
	v_cndmask_b32_e64 v57, v212, v57, s[4:5]
	v_cndmask_b32_e64 v41, v212, v41, s[6:7]
	v_cndmask_b32_e64 v58, v212, v58, s[8:9]
	v_add_u32_e32 v96, 0x45, v156
	v_add_u32_e32 v127, 0x64, v156
	v_add_u32_e32 v128, 0x44, v156
	v_cmp_gt_u32_e64 s[4:5], s11, v96
	v_cmp_gt_u32_e64 s[6:7], s11, v127
	v_cmp_gt_u32_e64 s[8:9], s11, v128
	v_cndmask_b32_e64 v42, v212, v42, s[4:5]
	v_cndmask_b32_e64 v59, v212, v59, s[6:7]
	v_cndmask_b32_e64 v43, v212, v43, s[8:9]
	v_add_u32_e32 v96, 0x63, v156
	v_add_u32_e32 v127, 0x43, v156
	v_add_u32_e32 v128, 0x62, v156
	v_cmp_gt_u32_e64 s[4:5], s11, v96
	v_cmp_gt_u32_e64 s[6:7], s11, v127
	v_cmp_gt_u32_e64 s[8:9], s11, v128
	v_cndmask_b32_e64 v60, v212, v60, s[4:5]
	v_cndmask_b32_e64 v44, v212, v44, s[6:7]
	v_cndmask_b32_e64 v61, v212, v61, s[8:9]
	v_add_u32_e32 v96, 0x42, v156
	v_add_u32_e32 v127, 0x61, v156
	v_add_u32_e32 v128, 0x41, v156
	v_cmp_gt_u32_e64 s[4:5], s11, v96
	v_cmp_gt_u32_e64 s[6:7], s11, v127
	v_cmp_gt_u32_e64 s[8:9], s11, v128
	v_cndmask_b32_e64 v45, v212, v45, s[4:5]
	v_cndmask_b32_e64 v62, v212, v62, s[6:7]
	v_cndmask_b32_e64 v46, v212, v46, s[8:9]
	v_add_u32_e32 v96, 0x60, v156
	v_add_u32_e32 v127, 64, v156
	v_cmp_gt_u32_e64 s[4:5], s11, v96
	v_cmp_gt_u32_e64 s[6:7], s11, v127
	s_nop 0
	v_cndmask_b32_e64 v63, v212, v63, s[4:5]
	v_cndmask_b32_e64 v47, v212, v47, s[6:7]

.LBB0_191:
	v_sub_f32_e32 v48, v48, v127
	v_sub_f32_e32 v32, v32, v127
	v_exp_f32_e32 v136, v48
	v_exp_f32_e32 v137, v32
	v_sub_f32_e32 v32, v49, v127
	v_sub_f32_e32 v33, v33, v127
	v_exp_f32_e32 v32, v32
	v_exp_f32_e32 v96, v33
	v_add_f32_e32 v33, v136, v137
	v_sub_f32_e32 v34, v34, v127
	v_exp_f32_e32 v138, v34
	v_pk_add_f32 v[48:49], v[32:33], v[96:97]
	v_sub_f32_e32 v33, v50, v127
	v_pk_add_f32 v[48:49], v[48:49], v[48:49] op_sel_hi:[0,1]
	v_exp_f32_e32 v33, v33
	v_sub_f32_e32 v34, v51, v127
	v_sub_f32_e32 v35, v35, v127
	v_exp_f32_e32 v34, v34
	v_exp_f32_e32 v48, v35
	v_add_f32_e32 v35, v33, v138
	v_sub_f32_e32 v36, v36, v127
	v_sub_f32_e32 v37, v37, v127
	v_pk_add_f32 v[50:51], v[34:35], v[48:49]
	v_sub_f32_e32 v35, v52, v127
	v_pk_add_f32 v[50:51], v[50:51], v[50:51] op_sel_hi:[0,1]
	v_exp_f32_e32 v35, v35
	v_exp_f32_e32 v49, v36
	v_sub_f32_e32 v36, v53, v127
	v_exp_f32_e32 v36, v36
	v_exp_f32_e32 v50, v37
	v_add_f32_e32 v37, v35, v49
	v_sub_f32_e32 v38, v38, v127
	v_sub_f32_e32 v39, v39, v127
	v_pk_add_f32 v[52:53], v[36:37], v[50:51]
	v_sub_f32_e32 v37, v54, v127
	v_pk_add_f32 v[52:53], v[52:53], v[52:53] op_sel_hi:[0,1]
	v_exp_f32_e32 v37, v37
	v_exp_f32_e32 v51, v38
	v_sub_f32_e32 v38, v55, v127
	v_exp_f32_e32 v38, v38
	v_exp_f32_e32 v52, v39
	v_add_f32_e32 v39, v37, v51
	v_cvt_pk_bf16_f32 v33, v33, v34
	v_cvt_pk_bf16_f32 v34, v35, v36
	v_pk_add_f32 v[54:55], v[38:39], v[52:53]
	v_sub_f32_e32 v39, v56, v127
	v_exp_f32_e32 v53, v39
	v_sub_f32_e32 v39, v40, v127
	v_exp_f32_e32 v139, v39
	v_sub_f32_e32 v39, v57, v127
	v_pk_add_f32 v[128:129], v[54:55], v[54:55] op_sel_hi:[0,1]
	v_exp_f32_e32 v40, v39
	v_sub_f32_e32 v39, v41, v127
	v_exp_f32_e32 v128, v39
	v_add_f32_e32 v41, v53, v139
	v_sub_f32_e32 v39, v58, v127
	v_cvt_pk_bf16_f32 v35, v37, v38
	v_pk_add_f32 v[54:55], v[40:41], v[128:129]
	v_exp_f32_e32 v41, v39
	v_sub_f32_e32 v39, v42, v127
	v_exp_f32_e32 v129, v39
	v_sub_f32_e32 v39, v59, v127
	v_pk_add_f32 v[130:131], v[54:55], v[54:55] op_sel_hi:[0,1]
	v_exp_f32_e32 v42, v39
	v_sub_f32_e32 v39, v43, v127
	v_exp_f32_e32 v130, v39
	v_add_f32_e32 v43, v41, v129
	v_sub_f32_e32 v39, v60, v127
	v_cvt_pk_bf16_f32 v37, v138, v48
	v_pk_add_f32 v[54:55], v[42:43], v[130:131]
	v_exp_f32_e32 v43, v39
	v_sub_f32_e32 v39, v44, v127
	v_exp_f32_e32 v131, v39
	v_sub_f32_e32 v39, v61, v127
	v_pk_add_f32 v[132:133], v[54:55], v[54:55] op_sel_hi:[0,1]
	v_exp_f32_e32 v44, v39
	v_sub_f32_e32 v39, v45, v127
	v_exp_f32_e32 v132, v39
	v_add_f32_e32 v45, v43, v131
	v_sub_f32_e32 v39, v62, v127
	v_cvt_pk_bf16_f32 v38, v49, v50
	v_pk_add_f32 v[54:55], v[44:45], v[132:133]
	v_exp_f32_e32 v45, v39
	v_sub_f32_e32 v39, v46, v127
	v_exp_f32_e32 v133, v39
	v_sub_f32_e32 v39, v63, v127
	v_pk_add_f32 v[134:135], v[54:55], v[54:55] op_sel_hi:[0,1]
	v_exp_f32_e32 v46, v39
	v_sub_f32_e32 v39, v47, v127
	v_exp_f32_e32 v134, v39
	v_add_f32_e32 v47, v45, v133
	v_cvt_pk_bf16_f32 v40, v53, v40
	v_cvt_pk_bf16_f32 v41, v41, v42
	v_pk_add_f32 v[54:55], v[46:47], v[134:135]
	v_cvt_pk_bf16_f32 v42, v43, v44
	v_add_f32_e32 v39, v54, v55
	v_add_f32_e32 v115, v115, v39
	v_cvt_pk_bf16_f32 v39, v51, v52
	v_cvt_pk_bf16_f32 v43, v45, v46
	ds_read_b128 v[44:47], v126 offset:13824
	ds_read_b128 v[48:51], v126 offset:13856
	ds_read_b128 v[52:55], v126 offset:13888
	ds_read_b128 v[56:59], v126 offset:13920
	v_cvt_pk_bf16_f32 v32, v136, v32
	v_cvt_pk_bf16_f32 v36, v137, v96
	v_cvt_pk_bf16_f32 v60, v139, v128
	v_cvt_pk_bf16_f32 v61, v129, v130
	v_cvt_pk_bf16_f32 v62, v131, v132
	v_cvt_pk_bf16_f32 v63, v133, v134
	s_nop 0
	s_waitcnt lgkmcnt(7)
	v_mfma_f32_32x32x16_bf16 v[16:31], v[110:113], v[32:35], v[16:31]
	s_waitcnt lgkmcnt(6)
	v_mfma_f32_32x32x16_bf16 v[16:31], v[106:109], v[40:43], v[16:31]
	s_waitcnt lgkmcnt(5)
	v_mfma_f32_32x32x16_bf16 v[16:31], v[102:105], v[36:39], v[16:31]
	s_waitcnt lgkmcnt(4)
	v_mfma_f32_32x32x16_bf16 v[16:31], v[98:101], v[60:63], v[16:31]
	s_nop 0
	s_nop 0
	s_waitcnt lgkmcnt(3)
	v_mfma_f32_32x32x16_bf16 v[0:15], v[44:47], v[32:35], v[0:15]
	s_waitcnt lgkmcnt(2)
	v_mfma_f32_32x32x16_bf16 v[0:15], v[48:51], v[40:43], v[0:15]
	s_waitcnt lgkmcnt(1)
	v_mfma_f32_32x32x16_bf16 v[0:15], v[52:55], v[36:39], v[0:15]
	s_waitcnt lgkmcnt(0)
	v_mfma_f32_32x32x16_bf16 v[0:15], v[56:59], v[60:63], v[0:15]
	s_nop 0

.LBB0_202:
	v_add_u32_e32 v40, v122, v116
	ds_read_b128 v[32:35], v40 offset:18432
	ds_read_b128 v[98:101], v40 offset:18464
	ds_read_b128 v[36:39], v40 offset:23040
	ds_read_b128 v[102:105], v40 offset:23072
	ds_read_b128 v[106:109], v40 offset:18496
	ds_read_b128 v[110:113], v40 offset:18528
	ds_read_b128 v[126:129], v40 offset:23104
	ds_read_b128 v[130:133], v40 offset:23136
	s_nop 0
	s_nop 0
	s_waitcnt lgkmcnt(7)
	v_mfma_f32_32x32x16_bf16 v[48:63], v[32:35], v[64:67], 0
	s_waitcnt lgkmcnt(5)
	v_mfma_f32_32x32x16_bf16 v[32:47], v[36:39], v[64:67], 0
	v_mfma_f32_32x32x16_bf16 v[48:63], v[98:101], v[68:71], v[48:63]
	s_waitcnt lgkmcnt(4)
	v_mfma_f32_32x32x16_bf16 v[32:47], v[102:105], v[68:71], v[32:47]
	s_waitcnt lgkmcnt(3)
	v_mfma_f32_32x32x16_bf16 v[48:63], v[106:109], v[72:75], v[48:63]
	s_waitcnt lgkmcnt(1)
	v_mfma_f32_32x32x16_bf16 v[32:47], v[126:129], v[72:75], v[32:47]
	v_add_u32_e32 v126, v123, v116
	v_mfma_f32_32x32x16_bf16 v[48:63], v[110:113], v[76:79], v[48:63]
	ds_read_b128 v[110:113], v126 offset:27648
	ds_read_b128 v[106:109], v126 offset:27680
	ds_read_b128 v[102:105], v126 offset:27712
	ds_read_b128 v[98:101], v126 offset:27744
	s_waitcnt lgkmcnt(4)
	v_mfma_f32_32x32x16_bf16 v[32:47], v[130:133], v[76:79], v[32:47]
	s_and_b64 vcc, exec, s[0:1]
	s_cbranch_vccnz .LBB0_204
	s_add_i32 s10, s27, -1
	v_add_u32_e32 v156, s10, v124
	s_lshl_b32 s11, s27, 1
	s_add_i32 s11, s11, -1
	v_add_u32_e32 v96, 55, v156
	v_add_u32_e32 v127, 23, v156
	v_add_u32_e32 v128, 54, v156
	v_cmp_gt_u32_e64 s[4:5], s11, v96
	v_cmp_gt_u32_e64 s[6:7], s11, v127
	v_cmp_gt_u32_e64 s[8:9], s11, v128
	v_cndmask_b32_e64 v48, v212, v48, s[4:5]
	v_cndmask_b32_e64 v32, v212, v32, s[6:7]
	v_cndmask_b32_e64 v49, v212, v49, s[8:9]
	v_add_u32_e32 v96, 22, v156
	v_add_u32_e32 v127, 53, v156
	v_add_u32_e32 v128, 21, v156
	v_cmp_gt_u32_e64 s[4:5], s11, v96
	v_cmp_gt_u32_e64 s[6:7], s11, v127
	v_cmp_gt_u32_e64 s[8:9], s11, v128
	v_cndmask_b32_e64 v33, v212, v33, s[4:5]
	v_cndmask_b32_e64 v50, v212, v50, s[6:7]
	v_cndmask_b32_e64 v34, v212, v34, s[8:9]
	v_add_u32_e32 v96, 52, v156
	v_add_u32_e32 v127, 20, v156
	v_add_u32_e32 v128, 51, v156
	v_cmp_gt_u32_e64 s[4:5], s11, v96
	v_cmp_gt_u32_e64 s[6:7], s11, v127
	v_cmp_gt_u32_e64 s[8:9], s11, v128
	v_cndmask_b32_e64 v51, v212, v51, s[4:5]
	v_cndmask_b32_e64 v35, v212, v35, s[6:7]
	v_cndmask_b32_e64 v52, v212, v52, s[8:9]
	v_add_u32_e32 v96, 19, v156
	v_add_u32_e32 v127, 50, v156
	v_add_u32_e32 v128, 18, v156
	v_cmp_gt_u32_e64 s[4:5], s11, v96
	v_cmp_gt_u32_e64 s[6:7], s11, v127
	v_cmp_gt_u32_e64 s[8:9], s11, v128
	v_cndmask_b32_e64 v36, v212, v36, s[4:5]
	v_cndmask_b32_e64 v53, v212, v53, s[6:7]
	v_cndmask_b32_e64 v37, v212, v37, s[8:9]
	v_add_u32_e32 v96, 49, v156
	v_add_u32_e32 v127, 17, v156
	v_add_u32_e32 v128, 48, v156
	v_cmp_gt_u32_e64 s[4:5], s11, v96
	v_cmp_gt_u32_e64 s[6:7], s11, v127
	v_cmp_gt_u32_e64 s[8:9], s11, v128
	v_cndmask_b32_e64 v54, v212, v54, s[4:5]
	v_cndmask_b32_e64 v38, v212, v38, s[6:7]
	v_cndmask_b32_e64 v55, v212, v55, s[8:9]
	v_add_u32_e32 v96, 16, v156
	v_add_u32_e32 v127, 39, v156
	v_add_u32_e32 v128, 7, v156
	v_cmp_gt_u32_e64 s[4:5], s11, v96
	v_cmp_gt_u32_e64 s[6:7], s11, v127
	v_cmp_gt_u32_e64 s[8:9], s11, v128
	v_cndmask_b32_e64 v39, v212, v39, s[4:5]
	v_cndmask_b32_e64 v56, v212, v56, s[6:7]
	v_cndmask_b32_e64 v40, v212, v40, s[8:9]
	v_add_u32_e32 v96, 38, v156
	v_add_u32_e32 v127, 6, v156
	v_add_u32_e32 v128, 37, v156
	v_cmp_gt_u32_e64 s[4:5], s11, v96
	v_cmp_gt_u32_e64 s[6:7], s11, v127
	v_cmp_gt_u32_e64 s[8:9], s11, v128
	v_cndmask_b32_e64 v57, v212, v57, s[4:5]
	v_cndmask_b32_e64 v41, v212, v41, s[6:7]
	v_cndmask_b32_e64 v58, v212, v58, s[8:9]
	v_add_u32_e32 v96, 5, v156
	v_add_u32_e32 v127, 36, v156
	v_add_u32_e32 v128, 4, v156
	v_cmp_gt_u32_e64 s[4:5], s11, v96
	v_cmp_gt_u32_e64 s[6:7], s11, v127
	v_cmp_gt_u32_e64 s[8:9], s11, v128
	v_cndmask_b32_e64 v42, v212, v42, s[4:5]
	v_cndmask_b32_e64 v59, v212, v59, s[6:7]
	v_cndmask_b32_e64 v43, v212, v43, s[8:9]
	v_add_u32_e32 v96, 35, v156
	v_add_u32_e32 v127, 3, v156
	v_add_u32_e32 v128, 34, v156
	v_cmp_gt_u32_e64 s[4:5], s11, v96
	v_cmp_gt_u32_e64 s[6:7], s11, v127
	v_cmp_gt_u32_e64 s[8:9], s11, v128
	v_cndmask_b32_e64 v60, v212, v60, s[4:5]
	v_cndmask_b32_e64 v44, v212, v44, s[6:7]
	v_cndmask_b32_e64 v61, v212, v61, s[8:9]
	v_add_u32_e32 v96, 2, v156
	v_add_u32_e32 v127, 33, v156
	v_add_u32_e32 v128, 1, v156
	v_cmp_gt_u32_e64 s[4:5], s11, v96
	v_cmp_gt_u32_e64 s[6:7], s11, v127
	v_cmp_gt_u32_e64 s[8:9], s11, v128
	v_cndmask_b32_e64 v45, v212, v45, s[4:5]
	v_cndmask_b32_e64 v62, v212, v62, s[6:7]
	v_cndmask_b32_e64 v46, v212, v46, s[8:9]
	v_add_u32_e32 v96, 32, v156
	v_add_u32_e32 v127, 0, v156
	v_cmp_gt_u32_e64 s[4:5], s11, v96
	v_cmp_gt_u32_e64 s[6:7], s11, v127
	s_nop 0
	v_cndmask_b32_e64 v63, v212, v63, s[4:5]
	v_cndmask_b32_e64 v47, v212, v47, s[6:7]

.LBB0_207:
	v_sub_f32_e32 v48, v48, v127
	v_sub_f32_e32 v32, v32, v127
	v_exp_f32_e32 v136, v48
	v_exp_f32_e32 v137, v32
	v_sub_f32_e32 v32, v49, v127
	v_sub_f32_e32 v33, v33, v127
	v_exp_f32_e32 v32, v32
	v_exp_f32_e32 v96, v33
	v_add_f32_e32 v33, v136, v137
	v_sub_f32_e32 v34, v34, v127
	v_exp_f32_e32 v138, v34
	v_pk_add_f32 v[48:49], v[32:33], v[96:97]
	v_sub_f32_e32 v33, v50, v127
	v_pk_add_f32 v[48:49], v[48:49], v[48:49] op_sel_hi:[0,1]
	v_exp_f32_e32 v33, v33
	v_sub_f32_e32 v34, v51, v127
	v_sub_f32_e32 v35, v35, v127
	v_exp_f32_e32 v34, v34
	v_exp_f32_e32 v48, v35
	v_add_f32_e32 v35, v33, v138
	v_sub_f32_e32 v36, v36, v127
	v_sub_f32_e32 v37, v37, v127
	v_pk_add_f32 v[50:51], v[34:35], v[48:49]
	v_sub_f32_e32 v35, v52, v127
	v_pk_add_f32 v[50:51], v[50:51], v[50:51] op_sel_hi:[0,1]
	v_exp_f32_e32 v35, v35
	v_exp_f32_e32 v49, v36
	v_sub_f32_e32 v36, v53, v127
	v_exp_f32_e32 v36, v36
	v_exp_f32_e32 v50, v37
	v_add_f32_e32 v37, v35, v49
	v_sub_f32_e32 v38, v38, v127
	v_sub_f32_e32 v39, v39, v127
	v_pk_add_f32 v[52:53], v[36:37], v[50:51]
	v_sub_f32_e32 v37, v54, v127
	v_pk_add_f32 v[52:53], v[52:53], v[52:53] op_sel_hi:[0,1]
	v_exp_f32_e32 v37, v37
	v_exp_f32_e32 v51, v38
	v_sub_f32_e32 v38, v55, v127
	v_exp_f32_e32 v38, v38
	v_exp_f32_e32 v52, v39
	v_add_f32_e32 v39, v37, v51
	v_cvt_pk_bf16_f32 v33, v33, v34
	v_cvt_pk_bf16_f32 v34, v35, v36
	v_pk_add_f32 v[54:55], v[38:39], v[52:53]
	v_sub_f32_e32 v39, v56, v127
	v_exp_f32_e32 v53, v39
	v_sub_f32_e32 v39, v40, v127
	v_exp_f32_e32 v139, v39
	v_sub_f32_e32 v39, v57, v127
	v_pk_add_f32 v[128:129], v[54:55], v[54:55] op_sel_hi:[0,1]
	v_exp_f32_e32 v40, v39
	v_sub_f32_e32 v39, v41, v127
	v_exp_f32_e32 v128, v39
	v_add_f32_e32 v41, v53, v139
	v_sub_f32_e32 v39, v58, v127
	v_cvt_pk_bf16_f32 v35, v37, v38
	v_pk_add_f32 v[54:55], v[40:41], v[128:129]
	v_exp_f32_e32 v41, v39
	v_sub_f32_e32 v39, v42, v127
	v_exp_f32_e32 v129, v39
	v_sub_f32_e32 v39, v59, v127
	v_pk_add_f32 v[130:131], v[54:55], v[54:55] op_sel_hi:[0,1]
	v_exp_f32_e32 v42, v39
	v_sub_f32_e32 v39, v43, v127
	v_exp_f32_e32 v130, v39
	v_add_f32_e32 v43, v41, v129
	v_sub_f32_e32 v39, v60, v127
	v_cvt_pk_bf16_f32 v37, v138, v48
	v_pk_add_f32 v[54:55], v[42:43], v[130:131]
	v_exp_f32_e32 v43, v39
	v_sub_f32_e32 v39, v44, v127
	v_exp_f32_e32 v131, v39
	v_sub_f32_e32 v39, v61, v127
	v_pk_add_f32 v[132:133], v[54:55], v[54:55] op_sel_hi:[0,1]
	v_exp_f32_e32 v44, v39
	v_sub_f32_e32 v39, v45, v127
	v_exp_f32_e32 v132, v39
	v_add_f32_e32 v45, v43, v131
	v_sub_f32_e32 v39, v62, v127
	v_cvt_pk_bf16_f32 v38, v49, v50
	v_pk_add_f32 v[54:55], v[44:45], v[132:133]
	v_exp_f32_e32 v45, v39
	v_sub_f32_e32 v39, v46, v127
	v_exp_f32_e32 v133, v39
	v_sub_f32_e32 v39, v63, v127
	v_pk_add_f32 v[134:135], v[54:55], v[54:55] op_sel_hi:[0,1]
	v_exp_f32_e32 v46, v39
	v_sub_f32_e32 v39, v47, v127
	v_exp_f32_e32 v134, v39
	v_add_f32_e32 v47, v45, v133
	v_cvt_pk_bf16_f32 v40, v53, v40
	v_cvt_pk_bf16_f32 v41, v41, v42
	v_pk_add_f32 v[54:55], v[46:47], v[134:135]
	v_cvt_pk_bf16_f32 v42, v43, v44
	v_add_f32_e32 v39, v54, v55
	v_add_f32_e32 v115, v115, v39
	v_cvt_pk_bf16_f32 v39, v51, v52
	v_cvt_pk_bf16_f32 v43, v45, v46
	ds_read_b128 v[44:47], v126 offset:32256
	ds_read_b128 v[48:51], v126 offset:32288
	ds_read_b128 v[52:55], v126 offset:32320
	ds_read_b128 v[56:59], v126 offset:32352
	v_cvt_pk_bf16_f32 v32, v136, v32
	v_cvt_pk_bf16_f32 v36, v137, v96
	v_cvt_pk_bf16_f32 v60, v139, v128
	v_cvt_pk_bf16_f32 v61, v129, v130
	v_cvt_pk_bf16_f32 v62, v131, v132
	v_cvt_pk_bf16_f32 v63, v133, v134
	s_nop 0
	s_waitcnt lgkmcnt(7)
	v_mfma_f32_32x32x16_bf16 v[16:31], v[110:113], v[32:35], v[16:31]
	s_waitcnt lgkmcnt(6)
	v_mfma_f32_32x32x16_bf16 v[16:31], v[106:109], v[40:43], v[16:31]
	s_waitcnt lgkmcnt(5)
	v_mfma_f32_32x32x16_bf16 v[16:31], v[102:105], v[36:39], v[16:31]
	s_waitcnt lgkmcnt(4)
	v_mfma_f32_32x32x16_bf16 v[16:31], v[98:101], v[60:63], v[16:31]
	s_nop 0
	s_nop 0
	s_waitcnt lgkmcnt(3)
	v_mfma_f32_32x32x16_bf16 v[0:15], v[44:47], v[32:35], v[0:15]
	s_waitcnt lgkmcnt(2)
	v_mfma_f32_32x32x16_bf16 v[0:15], v[48:51], v[40:43], v[0:15]
	s_waitcnt lgkmcnt(1)
	v_mfma_f32_32x32x16_bf16 v[0:15], v[52:55], v[36:39], v[0:15]
	s_waitcnt lgkmcnt(0)
	v_mfma_f32_32x32x16_bf16 v[0:15], v[56:59], v[60:63], v[0:15]
	s_nop 0

.LBB0_242:
	ds_read_b128 v[64:67], v183
	ds_read_b128 v[146:149], v183 offset:32
	ds_read_b128 v[68:71], v183 offset:4608
	ds_read_b128 v[150:153], v183 offset:4640
	ds_read_b128 v[154:157], v183 offset:64
	ds_read_b128 v[158:161], v183 offset:96
	ds_read_b128 v[166:169], v183 offset:4672
	ds_read_b128 v[188:191], v183 offset:4704
	s_nop 0
	s_nop 0
	s_waitcnt lgkmcnt(7)
	v_mfma_f32_32x32x16_bf16 v[80:95], v[64:67], v[98:101], 0
	s_waitcnt lgkmcnt(5)
	v_mfma_f32_32x32x16_bf16 v[64:79], v[68:71], v[98:101], 0
	v_mfma_f32_32x32x16_bf16 v[80:95], v[146:149], v[102:105], v[80:95]
	s_waitcnt lgkmcnt(4)
	v_mfma_f32_32x32x16_bf16 v[64:79], v[150:153], v[102:105], v[64:79]
	s_waitcnt lgkmcnt(3)
	v_mfma_f32_32x32x16_bf16 v[80:95], v[154:157], v[106:109], v[80:95]
	s_waitcnt lgkmcnt(1)
	v_mfma_f32_32x32x16_bf16 v[64:79], v[166:169], v[106:109], v[64:79]
	v_mfma_f32_32x32x16_bf16 v[80:95], v[158:161], v[110:113], v[80:95]
	ds_read_b128 v[158:161], v184 offset:18432
	ds_read_b128 v[154:157], v184 offset:18464
	ds_read_b128 v[150:153], v184 offset:18496
	ds_read_b128 v[146:149], v184 offset:18528
	s_waitcnt lgkmcnt(4)
	v_mfma_f32_32x32x16_bf16 v[64:79], v[188:191], v[110:113], v[64:79]
	s_nop 11
	v_max3_f32 v96, v64, v65, v66
	v_max3_f32 v96, v96, v67, v68
	v_max3_f32 v96, v96, v69, v70
	v_max3_f32 v96, v96, v71, v72
	v_max3_f32 v96, v96, v73, v74
	v_max3_f32 v96, v96, v75, v76
	v_max3_f32 v96, v96, v77, v78
	v_max3_f32 v96, v96, v79, v80
	v_max3_f32 v96, v96, v81, v82
	v_max3_f32 v96, v96, v83, v84
	v_max3_f32 v96, v96, v85, v86
	v_max3_f32 v96, v96, v87, v88
	v_max3_f32 v96, v96, v89, v90
	v_max3_f32 v96, v96, v91, v92
	v_max3_f32 v96, v96, v93, v94
	v_max_f32_e32 v96, v96, v95
	v_mov_b32_e32 v162, v96
	s_nop 1
	v_permlane32_swap_b32_e32 v96, v162
	v_max3_f32 v186, v187, v96, v162
	v_add_f32_e32 v96, 0x41000000, v187
	v_cmp_gt_f32_e32 vcc, v186, v96
	s_cbranch_vccz .LBB0_244
	v_sub_f32_e32 v96, v187, v186
	v_exp_f32_e32 v96, v96
	s_nop 0
	v_mul_f32_e32 v185, v185, v96
	v_pk_mul_f32 v[62:63], v[62:63], v[96:97] op_sel_hi:[1,0]
	v_pk_mul_f32 v[60:61], v[60:61], v[96:97] op_sel_hi:[1,0]
	v_pk_mul_f32 v[58:59], v[58:59], v[96:97] op_sel_hi:[1,0]
	v_pk_mul_f32 v[56:57], v[56:57], v[96:97] op_sel_hi:[1,0]
	v_pk_mul_f32 v[54:55], v[54:55], v[96:97] op_sel_hi:[1,0]
	v_pk_mul_f32 v[52:53], v[52:53], v[96:97] op_sel_hi:[1,0]
	v_pk_mul_f32 v[50:51], v[50:51], v[96:97] op_sel_hi:[1,0]
	v_pk_mul_f32 v[48:49], v[48:49], v[96:97] op_sel_hi:[1,0]
	v_pk_mul_f32 v[46:47], v[46:47], v[96:97] op_sel_hi:[1,0]
	v_pk_mul_f32 v[44:45], v[44:45], v[96:97] op_sel_hi:[1,0]
	v_pk_mul_f32 v[42:43], v[42:43], v[96:97] op_sel_hi:[1,0]
	v_pk_mul_f32 v[40:41], v[40:41], v[96:97] op_sel_hi:[1,0]
	v_pk_mul_f32 v[38:39], v[38:39], v[96:97] op_sel_hi:[1,0]
	v_pk_mul_f32 v[36:37], v[36:37], v[96:97] op_sel_hi:[1,0]
	v_pk_mul_f32 v[34:35], v[34:35], v[96:97] op_sel_hi:[1,0]
	v_pk_mul_f32 v[32:33], v[32:33], v[96:97] op_sel_hi:[1,0]
	v_pk_mul_f32 v[30:31], v[30:31], v[96:97] op_sel_hi:[1,0]
	v_pk_mul_f32 v[28:29], v[28:29], v[96:97] op_sel_hi:[1,0]
	v_pk_mul_f32 v[26:27], v[26:27], v[96:97] op_sel_hi:[1,0]
	v_pk_mul_f32 v[24:25], v[24:25], v[96:97] op_sel_hi:[1,0]
	v_pk_mul_f32 v[22:23], v[22:23], v[96:97] op_sel_hi:[1,0]
	v_pk_mul_f32 v[20:21], v[20:21], v[96:97] op_sel_hi:[1,0]
	v_pk_mul_f32 v[18:19], v[18:19], v[96:97] op_sel_hi:[1,0]
	v_pk_mul_f32 v[16:17], v[16:17], v[96:97] op_sel_hi:[1,0]
	v_pk_mul_f32 v[14:15], v[14:15], v[96:97] op_sel_hi:[1,0]
	v_pk_mul_f32 v[12:13], v[12:13], v[96:97] op_sel_hi:[1,0]
	v_pk_mul_f32 v[10:11], v[10:11], v[96:97] op_sel_hi:[1,0]
	v_pk_mul_f32 v[8:9], v[8:9], v[96:97] op_sel_hi:[1,0]
	v_pk_mul_f32 v[6:7], v[6:7], v[96:97] op_sel_hi:[1,0]
	v_pk_mul_f32 v[4:5], v[4:5], v[96:97] op_sel_hi:[1,0]
	v_pk_mul_f32 v[2:3], v[2:3], v[96:97] op_sel_hi:[1,0]
	v_pk_mul_f32 v[0:1], v[0:1], v[96:97] op_sel_hi:[1,0]
	s_branch .LBB0_245

.LBB0_245:
	ds_read_b128 v[196:199], v184 offset:23040
	ds_read_b128 v[200:203], v184 offset:23072
	ds_read_b128 v[206:209], v184 offset:23104
	ds_read_b128 v[216:219], v184 offset:23136
	v_sub_f32_e32 v80, v80, v186
	v_sub_f32_e32 v64, v64, v186
	v_sub_f32_e32 v81, v81, v186
	v_sub_f32_e32 v65, v65, v186
	v_sub_f32_e32 v82, v82, v186
	v_sub_f32_e32 v66, v66, v186
	v_sub_f32_e32 v83, v83, v186
	v_sub_f32_e32 v67, v67, v186
	v_sub_f32_e32 v84, v84, v186
	v_sub_f32_e32 v68, v68, v186
	v_sub_f32_e32 v85, v85, v186
	v_sub_f32_e32 v69, v69, v186
	v_sub_f32_e32 v86, v86, v186
	v_sub_f32_e32 v70, v70, v186
	v_sub_f32_e32 v87, v87, v186
	v_sub_f32_e32 v71, v71, v186
	v_sub_f32_e32 v88, v88, v186
	v_sub_f32_e32 v72, v72, v186
	v_sub_f32_e32 v89, v89, v186
	v_sub_f32_e32 v73, v73, v186
	v_sub_f32_e32 v90, v90, v186
	v_sub_f32_e32 v74, v74, v186
	v_sub_f32_e32 v91, v91, v186
	v_sub_f32_e32 v75, v75, v186
	v_sub_f32_e32 v92, v92, v186
	v_sub_f32_e32 v76, v76, v186
	v_sub_f32_e32 v93, v93, v186
	v_sub_f32_e32 v77, v77, v186
	v_sub_f32_e32 v94, v94, v186
	v_sub_f32_e32 v78, v78, v186
	v_sub_f32_e32 v95, v95, v186
	v_sub_f32_e32 v79, v79, v186
	v_exp_f32_e32 v80, v80
	v_exp_f32_e32 v64, v64
	v_exp_f32_e32 v81, v81
	v_exp_f32_e32 v65, v65
	v_exp_f32_e32 v82, v82
	v_exp_f32_e32 v66, v66
	v_exp_f32_e32 v83, v83
	v_exp_f32_e32 v67, v67
	v_exp_f32_e32 v84, v84
	v_exp_f32_e32 v68, v68
	v_exp_f32_e32 v85, v85
	v_exp_f32_e32 v69, v69
	v_exp_f32_e32 v86, v86
	v_exp_f32_e32 v70, v70
	v_exp_f32_e32 v87, v87
	v_exp_f32_e32 v71, v71
	v_exp_f32_e32 v88, v88
	v_exp_f32_e32 v72, v72
	v_exp_f32_e32 v89, v89
	v_exp_f32_e32 v73, v73
	v_exp_f32_e32 v90, v90
	v_exp_f32_e32 v74, v74
	v_exp_f32_e32 v91, v91
	v_exp_f32_e32 v75, v75
	v_exp_f32_e32 v92, v92
	v_exp_f32_e32 v76, v76
	v_exp_f32_e32 v93, v93
	v_exp_f32_e32 v77, v77
	v_exp_f32_e32 v94, v94
	v_exp_f32_e32 v78, v78
	v_exp_f32_e32 v95, v95
	v_exp_f32_e32 v79, v79
	v_cvt_pk_bf16_f32 v166, v80, v81
	v_cvt_pk_bf16_f32 v167, v82, v83
	v_cvt_pk_bf16_f32 v168, v84, v85
	v_cvt_pk_bf16_f32 v169, v86, v87
	v_cvt_pk_bf16_f32 v188, v64, v65
	v_cvt_pk_bf16_f32 v189, v66, v67
	v_cvt_pk_bf16_f32 v190, v68, v69
	v_cvt_pk_bf16_f32 v191, v70, v71
	v_cvt_pk_bf16_f32 v192, v88, v89
	v_cvt_pk_bf16_f32 v193, v90, v91
	v_cvt_pk_bf16_f32 v194, v92, v93
	v_cvt_pk_bf16_f32 v195, v94, v95
	v_cvt_pk_bf16_f32 v220, v72, v73
	v_cvt_pk_bf16_f32 v221, v74, v75
	v_cvt_pk_bf16_f32 v222, v76, v77
	v_cvt_pk_bf16_f32 v223, v78, v79
	s_nop 0
	s_waitcnt lgkmcnt(7)
	v_mfma_f32_32x32x16_bf16 v[48:63], v[158:161], v[166:169], v[48:63]
	s_waitcnt lgkmcnt(6)
	v_mfma_f32_32x32x16_bf16 v[48:63], v[154:157], v[192:195], v[48:63]
	s_waitcnt lgkmcnt(5)
	v_mfma_f32_32x32x16_bf16 v[48:63], v[150:153], v[188:191], v[48:63]
	s_waitcnt lgkmcnt(4)
	v_mfma_f32_32x32x16_bf16 v[48:63], v[146:149], v[220:223], v[48:63]
	s_nop 0
	ds_read_b128 v[146:149], v184 offset:27648
	ds_read_b128 v[150:153], v184 offset:27680
	ds_read_b128 v[154:157], v184 offset:27712
	ds_read_b128 v[158:161], v184 offset:27744
	s_nop 0
	s_waitcnt lgkmcnt(7)
	v_mfma_f32_32x32x16_bf16 v[32:47], v[196:199], v[166:169], v[32:47]
	s_waitcnt lgkmcnt(6)
	v_mfma_f32_32x32x16_bf16 v[32:47], v[200:203], v[192:195], v[32:47]
	s_waitcnt lgkmcnt(5)
	v_mfma_f32_32x32x16_bf16 v[32:47], v[206:209], v[188:191], v[32:47]
	s_waitcnt lgkmcnt(4)
	v_mfma_f32_32x32x16_bf16 v[32:47], v[216:219], v[220:223], v[32:47]
	s_nop 0
	ds_read_b128 v[196:199], v184 offset:32256
	ds_read_b128 v[200:203], v184 offset:32288
	ds_read_b128 v[206:209], v184 offset:32320
	ds_read_b128 v[216:219], v184 offset:32352
	s_nop 0
	s_waitcnt lgkmcnt(7)
	v_mfma_f32_32x32x16_bf16 v[16:31], v[146:149], v[166:169], v[16:31]
	s_waitcnt lgkmcnt(6)
	v_mfma_f32_32x32x16_bf16 v[16:31], v[150:153], v[192:195], v[16:31]
	s_waitcnt lgkmcnt(5)
	v_mfma_f32_32x32x16_bf16 v[16:31], v[154:157], v[188:191], v[16:31]
	s_waitcnt lgkmcnt(4)
	v_mfma_f32_32x32x16_bf16 v[16:31], v[158:161], v[220:223], v[16:31]
	s_nop 0
	s_nop 0
	s_waitcnt lgkmcnt(3)
	v_mfma_f32_32x32x16_bf16 v[0:15], v[196:199], v[166:169], v[0:15]
	s_waitcnt lgkmcnt(2)
	v_mfma_f32_32x32x16_bf16 v[0:15], v[200:203], v[192:195], v[0:15]
	s_waitcnt lgkmcnt(1)
	v_mfma_f32_32x32x16_bf16 v[0:15], v[206:209], v[188:191], v[0:15]
	s_waitcnt lgkmcnt(0)
	v_mfma_f32_32x32x16_bf16 v[0:15], v[216:219], v[220:223], v[0:15]
	s_nop 0
	v_mov_b32_e32 v146, v204
	s_andn2_b64 vcc, exec, s[52:53]
	v_lshrrev_b32_e32 v96, 3, v146
	v_mul_lo_u32 v147, v96, s55
	v_lshlrev_b32_e32 v96, 4, v146
	v_and_b32_e32 v96, 0x70, v96
	v_add3_u32 v148, 0, v147, v96
	v_add_u32_e32 v96, 0, v96
	v_add_u32_e32 v146, 0x200, v146
	v_add_u32_e32 v147, v96, v147
	v_lshrrev_b32_e32 v146, 3, v146
	s_waitcnt vmcnt(3)
	ds_write_b128 v148, v[114:117] offset:36864
	s_waitcnt vmcnt(2)
	ds_write_b128 v148, v[118:121] offset:46080
	s_waitcnt vmcnt(1)
	ds_write_b128 v147, v[122:125] offset:55296
	v_mad_u64_u32 v[146:147], s[0:1], v146, s55, v[96:97]
	v_cndmask_b32_e64 v96, 0, 1, s[52:53]
	v_cmp_ne_u32_e64 s[0:1], 1, v96
	s_waitcnt vmcnt(0)
	ds_write_b128 v146, v[126:129] offset:55296
	s_waitcnt lgkmcnt(0)
	s_barrier
	s_cbranch_vccnz .LBB0_247
	v_mov_b32_e32 v124, v204
	s_mov_b64 s[42:43], 0x6000
	v_ashrrev_i32_e32 v122, 3, v124
	v_lshlrev_b32_e32 v96, 4, v124
	v_add_u32_e32 v124, 0x200, v124
	v_ashrrev_i32_e32 v123, 31, v122
	v_ashrrev_i32_e32 v124, 3, v124
	v_lshlrev_b64 v[114:115], 7, v[122:123]
	v_ashrrev_i32_e32 v125, 31, v124
	v_lshl_add_u64 v[114:115], v[114:115], 0, s[42:43]
	v_lshlrev_b64 v[122:123], 9, v[122:123]
	v_lshlrev_b64 v[124:125], 9, v[124:125]
	v_lshl_add_u64 v[116:117], s[30:31], 0, v[114:115]
	v_and_b32_e32 v96, 0x70, v96
	v_lshl_add_u64 v[114:115], s[40:41], 0, v[114:115]
	v_lshl_add_u64 v[122:123], s[50:51], 0, v[122:123]
	v_lshl_add_u64 v[124:125], s[50:51], 0, v[124:125]
	v_lshl_add_u64 v[116:117], v[116:117], 0, v[96:97]
	v_lshl_add_u64 v[118:119], v[114:115], 0, v[96:97]
	v_lshl_add_u64 v[122:123], v[122:123], 0, v[96:97]
	v_lshl_add_u64 v[126:127], v[124:125], 0, v[96:97]
	global_load_dwordx4 v[114:117], v[116:117], off
	s_nop 0
	global_load_dwordx4 v[118:121], v[118:119], off
	s_nop 0
	global_load_dwordx4 v[122:125], v[122:123], off offset:384
	s_nop 0
	global_load_dwordx4 v[126:129], v[126:127], off offset:384
.LBB0_247:
	v_add_f32_e32 v64, v80, v64
	v_add_f32_e32 v64, 0, v64
	v_add_f32_e32 v65, v81, v65
	v_add_f32_e32 v64, v65, v64
	v_add_f32_e32 v65, v82, v66
	v_add_f32_e32 v64, v65, v64
	v_add_f32_e32 v65, v83, v67
	v_add_f32_e32 v64, v65, v64
	v_add_f32_e32 v65, v84, v68
	v_add_f32_e32 v64, v65, v64
	v_add_f32_e32 v65, v85, v69
	v_add_f32_e32 v64, v65, v64
	v_add_f32_e32 v65, v86, v70
	v_add_f32_e32 v64, v65, v64
	v_add_f32_e32 v65, v87, v71
	v_add_f32_e32 v64, v65, v64
	v_add_f32_e32 v65, v88, v72
	v_add_f32_e32 v64, v65, v64
	v_add_f32_e32 v65, v89, v73
	v_add_f32_e32 v64, v65, v64
	v_add_f32_e32 v65, v90, v74
	v_add_f32_e32 v64, v65, v64
	v_add_f32_e32 v65, v91, v75
	v_add_f32_e32 v64, v65, v64
	v_add_f32_e32 v65, v92, v76
	v_add_f32_e32 v64, v65, v64
	v_add_f32_e32 v65, v93, v77
	v_add_f32_e32 v64, v65, v64
	v_add_f32_e32 v65, v94, v78
	v_add_f32_e32 v64, v65, v64
	v_add_f32_e32 v65, v95, v79
	v_add_f32_e32 v64, v65, v64
	v_add_f32_e32 v96, v185, v64
	ds_read_b128 v[64:67], v183 offset:41472
	ds_read_b128 v[68:71], v183 offset:36864
	ds_read_b128 v[146:149], v183 offset:36896
	ds_read_b128 v[150:153], v183 offset:41504
	ds_read_b128 v[154:157], v183 offset:36928
	ds_read_b128 v[158:161], v183 offset:41536
	ds_read_b128 v[166:169], v183 offset:36960
	ds_read_b128 v[188:191], v183 offset:41568
	s_nop 0
	s_nop 0
	s_waitcnt lgkmcnt(6)
	v_mfma_f32_32x32x16_bf16 v[80:95], v[68:71], v[98:101], 0
	v_mfma_f32_32x32x16_bf16 v[64:79], v[64:67], v[98:101], 0
	s_waitcnt lgkmcnt(5)
	v_mfma_f32_32x32x16_bf16 v[80:95], v[146:149], v[102:105], v[80:95]
	s_waitcnt lgkmcnt(4)
	v_mfma_f32_32x32x16_bf16 v[64:79], v[150:153], v[102:105], v[64:79]
	s_waitcnt lgkmcnt(3)
	v_mfma_f32_32x32x16_bf16 v[80:95], v[154:157], v[106:109], v[80:95]
	s_waitcnt lgkmcnt(2)
	v_mfma_f32_32x32x16_bf16 v[64:79], v[158:161], v[106:109], v[64:79]
	ds_read_b128 v[158:161], v184 offset:55296
	ds_read_b128 v[154:157], v184 offset:55328
	ds_read_b128 v[150:153], v184 offset:55360
	ds_read_b128 v[146:149], v184 offset:55392
	s_waitcnt lgkmcnt(5)
	v_mfma_f32_32x32x16_bf16 v[80:95], v[166:169], v[110:113], v[80:95]
	s_waitcnt lgkmcnt(4)
	v_mfma_f32_32x32x16_bf16 v[64:79], v[188:191], v[110:113], v[64:79]
	s_nop 11
	v_max3_f32 v162, v64, v65, v66
	v_max3_f32 v162, v162, v67, v68
	v_max3_f32 v162, v162, v69, v70
	v_max3_f32 v162, v162, v71, v72
	v_max3_f32 v162, v162, v73, v74
	v_max3_f32 v162, v162, v75, v76
	v_max3_f32 v162, v162, v77, v78
	v_max3_f32 v162, v162, v79, v80
	v_max3_f32 v162, v162, v81, v82
	v_max3_f32 v162, v162, v83, v84
	v_max3_f32 v162, v162, v85, v86
	v_max3_f32 v162, v162, v87, v88
	v_max3_f32 v162, v162, v89, v90
	v_max3_f32 v162, v162, v91, v92
	v_max3_f32 v162, v162, v93, v94
	v_max_f32_e32 v162, v162, v95
	v_mov_b32_e32 v163, v162
	s_nop 1
	v_permlane32_swap_b32_e32 v162, v163
	v_max3_f32 v187, v186, v162, v163
	v_add_f32_e32 v162, 0x41000000, v186
	v_cmp_gt_f32_e32 vcc, v187, v162
	s_cbranch_vccz .LBB0_249
	v_sub_f32_e32 v162, v186, v187
	v_exp_f32_e32 v162, v162
	s_nop 0
	v_mul_f32_e32 v96, v96, v162
	v_pk_mul_f32 v[62:63], v[62:63], v[162:163] op_sel_hi:[1,0]
	v_pk_mul_f32 v[60:61], v[60:61], v[162:163] op_sel_hi:[1,0]
	v_pk_mul_f32 v[58:59], v[58:59], v[162:163] op_sel_hi:[1,0]
	v_pk_mul_f32 v[56:57], v[56:57], v[162:163] op_sel_hi:[1,0]
	v_pk_mul_f32 v[54:55], v[54:55], v[162:163] op_sel_hi:[1,0]
	v_pk_mul_f32 v[52:53], v[52:53], v[162:163] op_sel_hi:[1,0]
	v_pk_mul_f32 v[50:51], v[50:51], v[162:163] op_sel_hi:[1,0]
	v_pk_mul_f32 v[48:49], v[48:49], v[162:163] op_sel_hi:[1,0]
	v_pk_mul_f32 v[46:47], v[46:47], v[162:163] op_sel_hi:[1,0]
	v_pk_mul_f32 v[44:45], v[44:45], v[162:163] op_sel_hi:[1,0]
	v_pk_mul_f32 v[42:43], v[42:43], v[162:163] op_sel_hi:[1,0]
	v_pk_mul_f32 v[40:41], v[40:41], v[162:163] op_sel_hi:[1,0]
	v_pk_mul_f32 v[38:39], v[38:39], v[162:163] op_sel_hi:[1,0]
	v_pk_mul_f32 v[36:37], v[36:37], v[162:163] op_sel_hi:[1,0]
	v_pk_mul_f32 v[34:35], v[34:35], v[162:163] op_sel_hi:[1,0]
	v_pk_mul_f32 v[32:33], v[32:33], v[162:163] op_sel_hi:[1,0]
	v_pk_mul_f32 v[30:31], v[30:31], v[162:163] op_sel_hi:[1,0]
	v_pk_mul_f32 v[28:29], v[28:29], v[162:163] op_sel_hi:[1,0]
	v_pk_mul_f32 v[26:27], v[26:27], v[162:163] op_sel_hi:[1,0]
	v_pk_mul_f32 v[24:25], v[24:25], v[162:163] op_sel_hi:[1,0]
	v_pk_mul_f32 v[22:23], v[22:23], v[162:163] op_sel_hi:[1,0]
	v_pk_mul_f32 v[20:21], v[20:21], v[162:163] op_sel_hi:[1,0]
	v_pk_mul_f32 v[18:19], v[18:19], v[162:163] op_sel_hi:[1,0]
	v_pk_mul_f32 v[16:17], v[16:17], v[162:163] op_sel_hi:[1,0]
	v_pk_mul_f32 v[14:15], v[14:15], v[162:163] op_sel_hi:[1,0]
	v_pk_mul_f32 v[12:13], v[12:13], v[162:163] op_sel_hi:[1,0]
	v_pk_mul_f32 v[10:11], v[10:11], v[162:163] op_sel_hi:[1,0]
	v_pk_mul_f32 v[8:9], v[8:9], v[162:163] op_sel_hi:[1,0]
	v_pk_mul_f32 v[6:7], v[6:7], v[162:163] op_sel_hi:[1,0]
	v_pk_mul_f32 v[4:5], v[4:5], v[162:163] op_sel_hi:[1,0]
	v_pk_mul_f32 v[2:3], v[2:3], v[162:163] op_sel_hi:[1,0]
	v_pk_mul_f32 v[0:1], v[0:1], v[162:163] op_sel_hi:[1,0]
	s_branch .LBB0_250

.LBB0_250:
	ds_read_b128 v[196:199], v184 offset:59904
	ds_read_b128 v[200:203], v184 offset:59936
	ds_read_b128 v[206:209], v184 offset:59968
	ds_read_b128 v[216:219], v184 offset:60000
	v_sub_f32_e32 v80, v80, v187
	v_sub_f32_e32 v64, v64, v187
	v_sub_f32_e32 v81, v81, v187
	v_sub_f32_e32 v65, v65, v187
	v_sub_f32_e32 v82, v82, v187
	v_sub_f32_e32 v66, v66, v187
	v_sub_f32_e32 v83, v83, v187
	v_sub_f32_e32 v67, v67, v187
	v_sub_f32_e32 v84, v84, v187
	v_sub_f32_e32 v68, v68, v187
	v_sub_f32_e32 v85, v85, v187
	v_sub_f32_e32 v69, v69, v187
	v_sub_f32_e32 v86, v86, v187
	v_sub_f32_e32 v70, v70, v187
	v_sub_f32_e32 v87, v87, v187
	v_sub_f32_e32 v71, v71, v187
	v_sub_f32_e32 v88, v88, v187
	v_sub_f32_e32 v72, v72, v187
	v_sub_f32_e32 v89, v89, v187
	v_sub_f32_e32 v73, v73, v187
	v_sub_f32_e32 v90, v90, v187
	v_sub_f32_e32 v74, v74, v187
	v_sub_f32_e32 v91, v91, v187
	v_sub_f32_e32 v75, v75, v187
	v_sub_f32_e32 v92, v92, v187
	v_sub_f32_e32 v76, v76, v187
	v_sub_f32_e32 v93, v93, v187
	v_sub_f32_e32 v77, v77, v187
	v_sub_f32_e32 v94, v94, v187
	v_sub_f32_e32 v78, v78, v187
	v_sub_f32_e32 v95, v95, v187
	v_sub_f32_e32 v79, v79, v187
	v_exp_f32_e32 v80, v80
	v_exp_f32_e32 v64, v64
	v_exp_f32_e32 v81, v81
	v_exp_f32_e32 v65, v65
	v_exp_f32_e32 v82, v82
	v_exp_f32_e32 v66, v66
	v_exp_f32_e32 v83, v83
	v_exp_f32_e32 v67, v67
	v_exp_f32_e32 v84, v84
	v_exp_f32_e32 v68, v68
	v_exp_f32_e32 v85, v85
	v_exp_f32_e32 v69, v69
	v_exp_f32_e32 v86, v86
	v_exp_f32_e32 v70, v70
	v_exp_f32_e32 v87, v87
	v_exp_f32_e32 v71, v71
	v_exp_f32_e32 v88, v88
	v_exp_f32_e32 v72, v72
	v_exp_f32_e32 v89, v89
	v_exp_f32_e32 v73, v73
	v_exp_f32_e32 v90, v90
	v_exp_f32_e32 v74, v74
	v_exp_f32_e32 v91, v91
	v_exp_f32_e32 v75, v75
	v_exp_f32_e32 v92, v92
	v_exp_f32_e32 v76, v76
	v_exp_f32_e32 v93, v93
	v_exp_f32_e32 v77, v77
	v_exp_f32_e32 v94, v94
	v_exp_f32_e32 v78, v78
	v_exp_f32_e32 v95, v95
	v_exp_f32_e32 v79, v79
	v_cvt_pk_bf16_f32 v166, v80, v81
	v_cvt_pk_bf16_f32 v167, v82, v83
	v_cvt_pk_bf16_f32 v168, v84, v85
	v_cvt_pk_bf16_f32 v169, v86, v87
	v_cvt_pk_bf16_f32 v188, v64, v65
	v_cvt_pk_bf16_f32 v189, v66, v67
	v_cvt_pk_bf16_f32 v190, v68, v69
	v_cvt_pk_bf16_f32 v191, v70, v71
	v_cvt_pk_bf16_f32 v192, v88, v89
	v_cvt_pk_bf16_f32 v193, v90, v91
	v_cvt_pk_bf16_f32 v194, v92, v93
	v_cvt_pk_bf16_f32 v195, v94, v95
	v_cvt_pk_bf16_f32 v220, v72, v73
	v_cvt_pk_bf16_f32 v221, v74, v75
	v_cvt_pk_bf16_f32 v222, v76, v77
	v_cvt_pk_bf16_f32 v223, v78, v79
	s_nop 0
	s_waitcnt lgkmcnt(7)
	v_mfma_f32_32x32x16_bf16 v[48:63], v[158:161], v[166:169], v[48:63]
	s_waitcnt lgkmcnt(6)
	v_mfma_f32_32x32x16_bf16 v[48:63], v[154:157], v[192:195], v[48:63]
	s_waitcnt lgkmcnt(5)
	v_mfma_f32_32x32x16_bf16 v[48:63], v[150:153], v[188:191], v[48:63]
	s_waitcnt lgkmcnt(4)
	v_mfma_f32_32x32x16_bf16 v[48:63], v[146:149], v[220:223], v[48:63]
	s_nop 0
	ds_read_b128 v[146:149], v184 offset:64512
	ds_read_b128 v[150:153], v184 offset:64544
	ds_read_b128 v[154:157], v184 offset:64576
	ds_read_b128 v[158:161], v184 offset:64608
	s_nop 0
	s_waitcnt lgkmcnt(7)
	v_mfma_f32_32x32x16_bf16 v[32:47], v[196:199], v[166:169], v[32:47]
	s_waitcnt lgkmcnt(6)
	v_mfma_f32_32x32x16_bf16 v[32:47], v[200:203], v[192:195], v[32:47]
	s_waitcnt lgkmcnt(5)
	v_mfma_f32_32x32x16_bf16 v[32:47], v[206:209], v[188:191], v[32:47]
	s_waitcnt lgkmcnt(4)
	v_mfma_f32_32x32x16_bf16 v[32:47], v[216:219], v[220:223], v[32:47]
	s_nop 0
	ds_read_b128 v[196:199], v181
	ds_read_b128 v[200:203], v182 offset:32
	ds_read_b128 v[206:209], v182 offset:64
	ds_read_b128 v[216:219], v182 offset:96
	s_nop 0
	s_waitcnt lgkmcnt(7)
	v_mfma_f32_32x32x16_bf16 v[16:31], v[146:149], v[166:169], v[16:31]
	s_waitcnt lgkmcnt(6)
	v_mfma_f32_32x32x16_bf16 v[16:31], v[150:153], v[192:195], v[16:31]
	s_waitcnt lgkmcnt(5)
	v_mfma_f32_32x32x16_bf16 v[16:31], v[154:157], v[188:191], v[16:31]
	s_waitcnt lgkmcnt(4)
	v_mfma_f32_32x32x16_bf16 v[16:31], v[158:161], v[220:223], v[16:31]
	s_nop 0
	s_nop 0
	s_waitcnt lgkmcnt(3)
	v_mfma_f32_32x32x16_bf16 v[0:15], v[196:199], v[166:169], v[0:15]
	s_waitcnt lgkmcnt(2)
	v_mfma_f32_32x32x16_bf16 v[0:15], v[200:203], v[192:195], v[0:15]
	s_waitcnt lgkmcnt(1)
	v_mfma_f32_32x32x16_bf16 v[0:15], v[206:209], v[188:191], v[0:15]
	s_waitcnt lgkmcnt(0)
	v_mfma_f32_32x32x16_bf16 v[0:15], v[216:219], v[220:223], v[0:15]
	s_nop 0
	s_and_b64 vcc, exec, s[0:1]
	s_cbranch_vccnz .LBB0_241
	v_mov_b32_e32 v147, v204
	s_nop 0
	v_lshrrev_b32_e32 v146, 3, v147
	v_mul_lo_u32 v148, v146, s55
	v_lshlrev_b32_e32 v146, 4, v147
	v_and_b32_e32 v146, 0x70, v146
	v_add_u32_e32 v147, 0x200, v147
	v_add3_u32 v149, 0, v148, v146
	v_add_u32_e32 v146, 0, v146
	v_lshrrev_b32_e32 v147, 3, v147
	v_add_u32_e32 v148, v146, v148
	v_mad_u64_u32 v[146:147], s[0:1], v147, s55, v[146:147]
	s_waitcnt vmcnt(3)
	ds_write_b128 v149, v[130:133]
	s_waitcnt vmcnt(2)
	ds_write_b128 v149, v[134:137] offset:9216
	s_waitcnt vmcnt(1)
	ds_write_b128 v148, v[138:141] offset:18432
	s_waitcnt vmcnt(0)
	ds_write_b128 v146, v[142:145] offset:18432
	s_branch .LBB0_241

.LBB0_275:
	ds_read_b128 v[64:67], v183
	ds_read_b128 v[146:149], v183 offset:32
	ds_read_b128 v[68:71], v183 offset:4608
	ds_read_b128 v[150:153], v183 offset:4640
	ds_read_b128 v[154:157], v183 offset:64
	ds_read_b128 v[158:161], v183 offset:96
	ds_read_b128 v[166:169], v183 offset:4672
	ds_read_b128 v[188:191], v183 offset:4704
	s_nop 0
	s_nop 0
	s_waitcnt lgkmcnt(7)
	v_mfma_f32_32x32x16_bf16 v[80:95], v[64:67], v[98:101], 0
	s_waitcnt lgkmcnt(5)
	v_mfma_f32_32x32x16_bf16 v[64:79], v[68:71], v[98:101], 0
	v_mfma_f32_32x32x16_bf16 v[80:95], v[146:149], v[102:105], v[80:95]
	s_waitcnt lgkmcnt(4)
	v_mfma_f32_32x32x16_bf16 v[64:79], v[150:153], v[102:105], v[64:79]
	s_waitcnt lgkmcnt(3)
	v_mfma_f32_32x32x16_bf16 v[80:95], v[154:157], v[106:109], v[80:95]
	s_waitcnt lgkmcnt(1)
	v_mfma_f32_32x32x16_bf16 v[64:79], v[166:169], v[106:109], v[64:79]
	v_mfma_f32_32x32x16_bf16 v[80:95], v[158:161], v[110:113], v[80:95]
	ds_read_b128 v[158:161], v184 offset:18432
	ds_read_b128 v[154:157], v184 offset:18464
	ds_read_b128 v[150:153], v184 offset:18496
	ds_read_b128 v[146:149], v184 offset:18528
	s_waitcnt lgkmcnt(4)
	v_mfma_f32_32x32x16_bf16 v[64:79], v[188:191], v[110:113], v[64:79]
	s_nop 11
	v_max3_f32 v96, v64, v65, v66
	v_max3_f32 v96, v96, v67, v68
	v_max3_f32 v96, v96, v69, v70
	v_max3_f32 v96, v96, v71, v72
	v_max3_f32 v96, v96, v73, v74
	v_max3_f32 v96, v96, v75, v76
	v_max3_f32 v96, v96, v77, v78
	v_max3_f32 v96, v96, v79, v80
	v_max3_f32 v96, v96, v81, v82
	v_max3_f32 v96, v96, v83, v84
	v_max3_f32 v96, v96, v85, v86
	v_max3_f32 v96, v96, v87, v88
	v_max3_f32 v96, v96, v89, v90
	v_max3_f32 v96, v96, v91, v92
	v_max3_f32 v96, v96, v93, v94
	v_max_f32_e32 v96, v96, v95
	v_mov_b32_e32 v162, v96
	s_nop 1
	v_permlane32_swap_b32_e32 v96, v162
	v_max3_f32 v187, v186, v96, v162
	v_add_f32_e32 v96, 0x41000000, v186
	v_cmp_gt_f32_e32 vcc, v187, v96
	s_cbranch_vccz .LBB0_277
	v_sub_f32_e32 v96, v186, v187
	v_exp_f32_e32 v96, v96
	s_nop 0
	v_mul_f32_e32 v185, v185, v96
	v_pk_mul_f32 v[62:63], v[62:63], v[96:97] op_sel_hi:[1,0]
	v_pk_mul_f32 v[60:61], v[60:61], v[96:97] op_sel_hi:[1,0]
	v_pk_mul_f32 v[58:59], v[58:59], v[96:97] op_sel_hi:[1,0]
	v_pk_mul_f32 v[56:57], v[56:57], v[96:97] op_sel_hi:[1,0]
	v_pk_mul_f32 v[54:55], v[54:55], v[96:97] op_sel_hi:[1,0]
	v_pk_mul_f32 v[52:53], v[52:53], v[96:97] op_sel_hi:[1,0]
	v_pk_mul_f32 v[50:51], v[50:51], v[96:97] op_sel_hi:[1,0]
	v_pk_mul_f32 v[48:49], v[48:49], v[96:97] op_sel_hi:[1,0]
	v_pk_mul_f32 v[46:47], v[46:47], v[96:97] op_sel_hi:[1,0]
	v_pk_mul_f32 v[44:45], v[44:45], v[96:97] op_sel_hi:[1,0]
	v_pk_mul_f32 v[42:43], v[42:43], v[96:97] op_sel_hi:[1,0]
	v_pk_mul_f32 v[40:41], v[40:41], v[96:97] op_sel_hi:[1,0]
	v_pk_mul_f32 v[38:39], v[38:39], v[96:97] op_sel_hi:[1,0]
	v_pk_mul_f32 v[36:37], v[36:37], v[96:97] op_sel_hi:[1,0]
	v_pk_mul_f32 v[34:35], v[34:35], v[96:97] op_sel_hi:[1,0]
	v_pk_mul_f32 v[32:33], v[32:33], v[96:97] op_sel_hi:[1,0]
	v_pk_mul_f32 v[30:31], v[30:31], v[96:97] op_sel_hi:[1,0]
	v_pk_mul_f32 v[28:29], v[28:29], v[96:97] op_sel_hi:[1,0]
	v_pk_mul_f32 v[26:27], v[26:27], v[96:97] op_sel_hi:[1,0]
	v_pk_mul_f32 v[24:25], v[24:25], v[96:97] op_sel_hi:[1,0]
	v_pk_mul_f32 v[22:23], v[22:23], v[96:97] op_sel_hi:[1,0]
	v_pk_mul_f32 v[20:21], v[20:21], v[96:97] op_sel_hi:[1,0]
	v_pk_mul_f32 v[18:19], v[18:19], v[96:97] op_sel_hi:[1,0]
	v_pk_mul_f32 v[16:17], v[16:17], v[96:97] op_sel_hi:[1,0]
	v_pk_mul_f32 v[14:15], v[14:15], v[96:97] op_sel_hi:[1,0]
	v_pk_mul_f32 v[12:13], v[12:13], v[96:97] op_sel_hi:[1,0]
	v_pk_mul_f32 v[10:11], v[10:11], v[96:97] op_sel_hi:[1,0]
	v_pk_mul_f32 v[8:9], v[8:9], v[96:97] op_sel_hi:[1,0]
	v_pk_mul_f32 v[6:7], v[6:7], v[96:97] op_sel_hi:[1,0]
	v_pk_mul_f32 v[4:5], v[4:5], v[96:97] op_sel_hi:[1,0]
	v_pk_mul_f32 v[2:3], v[2:3], v[96:97] op_sel_hi:[1,0]
	v_pk_mul_f32 v[0:1], v[0:1], v[96:97] op_sel_hi:[1,0]
	s_branch .LBB0_278

.LBB0_278:
	ds_read_b128 v[196:199], v184 offset:23040
	ds_read_b128 v[200:203], v184 offset:23072
	ds_read_b128 v[206:209], v184 offset:23104
	ds_read_b128 v[216:219], v184 offset:23136
	v_sub_f32_e32 v80, v80, v187
	v_sub_f32_e32 v64, v64, v187
	v_sub_f32_e32 v81, v81, v187
	v_sub_f32_e32 v65, v65, v187
	v_sub_f32_e32 v82, v82, v187
	v_sub_f32_e32 v66, v66, v187
	v_sub_f32_e32 v83, v83, v187
	v_sub_f32_e32 v67, v67, v187
	v_sub_f32_e32 v84, v84, v187
	v_sub_f32_e32 v68, v68, v187
	v_sub_f32_e32 v85, v85, v187
	v_sub_f32_e32 v69, v69, v187
	v_sub_f32_e32 v86, v86, v187
	v_sub_f32_e32 v70, v70, v187
	v_sub_f32_e32 v87, v87, v187
	v_sub_f32_e32 v71, v71, v187
	v_sub_f32_e32 v88, v88, v187
	v_sub_f32_e32 v72, v72, v187
	v_sub_f32_e32 v89, v89, v187
	v_sub_f32_e32 v73, v73, v187
	v_sub_f32_e32 v90, v90, v187
	v_sub_f32_e32 v74, v74, v187
	v_sub_f32_e32 v91, v91, v187
	v_sub_f32_e32 v75, v75, v187
	v_sub_f32_e32 v92, v92, v187
	v_sub_f32_e32 v76, v76, v187
	v_sub_f32_e32 v93, v93, v187
	v_sub_f32_e32 v77, v77, v187
	v_sub_f32_e32 v94, v94, v187
	v_sub_f32_e32 v78, v78, v187
	v_sub_f32_e32 v95, v95, v187
	v_sub_f32_e32 v79, v79, v187
	v_exp_f32_e32 v80, v80
	v_exp_f32_e32 v64, v64
	v_exp_f32_e32 v81, v81
	v_exp_f32_e32 v65, v65
	v_exp_f32_e32 v82, v82
	v_exp_f32_e32 v66, v66
	v_exp_f32_e32 v83, v83
	v_exp_f32_e32 v67, v67
	v_exp_f32_e32 v84, v84
	v_exp_f32_e32 v68, v68
	v_exp_f32_e32 v85, v85
	v_exp_f32_e32 v69, v69
	v_exp_f32_e32 v86, v86
	v_exp_f32_e32 v70, v70
	v_exp_f32_e32 v87, v87
	v_exp_f32_e32 v71, v71
	v_exp_f32_e32 v88, v88
	v_exp_f32_e32 v72, v72
	v_exp_f32_e32 v89, v89
	v_exp_f32_e32 v73, v73
	v_exp_f32_e32 v90, v90
	v_exp_f32_e32 v74, v74
	v_exp_f32_e32 v91, v91
	v_exp_f32_e32 v75, v75
	v_exp_f32_e32 v92, v92
	v_exp_f32_e32 v76, v76
	v_exp_f32_e32 v93, v93
	v_exp_f32_e32 v77, v77
	v_exp_f32_e32 v94, v94
	v_exp_f32_e32 v78, v78
	v_exp_f32_e32 v95, v95
	v_exp_f32_e32 v79, v79
	v_cvt_pk_bf16_f32 v166, v80, v81
	v_cvt_pk_bf16_f32 v167, v82, v83
	v_cvt_pk_bf16_f32 v168, v84, v85
	v_cvt_pk_bf16_f32 v169, v86, v87
	v_cvt_pk_bf16_f32 v188, v64, v65
	v_cvt_pk_bf16_f32 v189, v66, v67
	v_cvt_pk_bf16_f32 v190, v68, v69
	v_cvt_pk_bf16_f32 v191, v70, v71
	v_cvt_pk_bf16_f32 v192, v88, v89
	v_cvt_pk_bf16_f32 v193, v90, v91
	v_cvt_pk_bf16_f32 v194, v92, v93
	v_cvt_pk_bf16_f32 v195, v94, v95
	v_cvt_pk_bf16_f32 v220, v72, v73
	v_cvt_pk_bf16_f32 v221, v74, v75
	v_cvt_pk_bf16_f32 v222, v76, v77
	v_cvt_pk_bf16_f32 v223, v78, v79
	s_nop 0
	s_waitcnt lgkmcnt(7)
	v_mfma_f32_32x32x16_bf16 v[48:63], v[158:161], v[166:169], v[48:63]
	s_waitcnt lgkmcnt(6)
	v_mfma_f32_32x32x16_bf16 v[48:63], v[154:157], v[192:195], v[48:63]
	s_waitcnt lgkmcnt(5)
	v_mfma_f32_32x32x16_bf16 v[48:63], v[150:153], v[188:191], v[48:63]
	s_waitcnt lgkmcnt(4)
	v_mfma_f32_32x32x16_bf16 v[48:63], v[146:149], v[220:223], v[48:63]
	s_nop 0
	ds_read_b128 v[146:149], v184 offset:27648
	ds_read_b128 v[150:153], v184 offset:27680
	ds_read_b128 v[154:157], v184 offset:27712
	ds_read_b128 v[158:161], v184 offset:27744
	s_nop 0
	s_waitcnt lgkmcnt(7)
	v_mfma_f32_32x32x16_bf16 v[32:47], v[196:199], v[166:169], v[32:47]
	s_waitcnt lgkmcnt(6)
	v_mfma_f32_32x32x16_bf16 v[32:47], v[200:203], v[192:195], v[32:47]
	s_waitcnt lgkmcnt(5)
	v_mfma_f32_32x32x16_bf16 v[32:47], v[206:209], v[188:191], v[32:47]
	s_waitcnt lgkmcnt(4)
	v_mfma_f32_32x32x16_bf16 v[32:47], v[216:219], v[220:223], v[32:47]
	s_nop 0
	ds_read_b128 v[196:199], v184 offset:32256
	ds_read_b128 v[200:203], v184 offset:32288
	ds_read_b128 v[206:209], v184 offset:32320
	ds_read_b128 v[216:219], v184 offset:32352
	s_nop 0
	s_waitcnt lgkmcnt(7)
	v_mfma_f32_32x32x16_bf16 v[16:31], v[146:149], v[166:169], v[16:31]
	s_waitcnt lgkmcnt(6)
	v_mfma_f32_32x32x16_bf16 v[16:31], v[150:153], v[192:195], v[16:31]
	s_waitcnt lgkmcnt(5)
	v_mfma_f32_32x32x16_bf16 v[16:31], v[154:157], v[188:191], v[16:31]
	s_waitcnt lgkmcnt(4)
	v_mfma_f32_32x32x16_bf16 v[16:31], v[158:161], v[220:223], v[16:31]
	s_nop 0
	s_nop 0
	s_waitcnt lgkmcnt(3)
	v_mfma_f32_32x32x16_bf16 v[0:15], v[196:199], v[166:169], v[0:15]
	s_waitcnt lgkmcnt(2)
	v_mfma_f32_32x32x16_bf16 v[0:15], v[200:203], v[192:195], v[0:15]
	s_waitcnt lgkmcnt(1)
	v_mfma_f32_32x32x16_bf16 v[0:15], v[206:209], v[188:191], v[0:15]
	s_waitcnt lgkmcnt(0)
	v_mfma_f32_32x32x16_bf16 v[0:15], v[216:219], v[220:223], v[0:15]
	s_nop 0
	v_mov_b32_e32 v146, v204
	s_cmp_gt_u32 s37, 36
	v_lshrrev_b32_e32 v96, 3, v146
	v_mul_lo_u32 v147, v96, s55
	v_lshlrev_b32_e32 v96, 4, v146
	v_and_b32_e32 v96, 0x70, v96
	v_add3_u32 v148, 0, v147, v96
	v_add_u32_e32 v96, 0, v96
	v_add_u32_e32 v146, 0x200, v146
	v_add_u32_e32 v147, v96, v147
	v_lshrrev_b32_e32 v146, 3, v146
	s_waitcnt vmcnt(3)
	ds_write_b128 v148, v[114:117] offset:36864
	s_waitcnt vmcnt(2)
	ds_write_b128 v148, v[118:121] offset:46080
	s_waitcnt vmcnt(1)
	ds_write_b128 v147, v[122:125] offset:55296
	v_mad_u64_u32 v[146:147], s[42:43], v146, s55, v[96:97]
	s_waitcnt vmcnt(0)
	ds_write_b128 v146, v[126:129] offset:55296
	s_waitcnt lgkmcnt(0)
	s_barrier
	s_cbranch_scc1 .LBB0_285
	s_cmp_gt_u32 s37, 4
	s_cbranch_scc0 .LBB0_281
	v_mov_b32_e32 v122, v204
	s_add_i32 s24, s37, -5
	s_mov_b64 s[50:51], 0
	s_branch .LBB0_282

.LBB0_285:
	v_add_f32_e32 v64, v80, v64
	v_add_f32_e32 v64, 0, v64
	v_add_f32_e32 v65, v81, v65
	v_add_f32_e32 v64, v65, v64
	v_add_f32_e32 v65, v82, v66
	v_add_f32_e32 v64, v65, v64
	v_add_f32_e32 v65, v83, v67
	v_add_f32_e32 v64, v65, v64
	v_add_f32_e32 v65, v84, v68
	v_add_f32_e32 v64, v65, v64
	v_add_f32_e32 v65, v85, v69
	v_add_f32_e32 v64, v65, v64
	v_add_f32_e32 v65, v86, v70
	v_add_f32_e32 v64, v65, v64
	v_add_f32_e32 v65, v87, v71
	v_add_f32_e32 v64, v65, v64
	v_add_f32_e32 v65, v88, v72
	v_add_f32_e32 v64, v65, v64
	v_add_f32_e32 v65, v89, v73
	v_add_f32_e32 v64, v65, v64
	v_add_f32_e32 v65, v90, v74
	v_add_f32_e32 v64, v65, v64
	v_add_f32_e32 v65, v91, v75
	v_add_f32_e32 v64, v65, v64
	v_add_f32_e32 v65, v92, v76
	v_add_f32_e32 v64, v65, v64
	v_add_f32_e32 v65, v93, v77
	v_add_f32_e32 v64, v65, v64
	v_add_f32_e32 v65, v94, v78
	v_add_f32_e32 v64, v65, v64
	v_add_f32_e32 v65, v95, v79
	v_add_f32_e32 v64, v65, v64
	v_add_f32_e32 v185, v185, v64
	ds_read_b128 v[64:67], v183 offset:41472
	ds_read_b128 v[68:71], v183 offset:36864
	ds_read_b128 v[146:149], v183 offset:36896
	ds_read_b128 v[150:153], v183 offset:41504
	ds_read_b128 v[154:157], v183 offset:36928
	ds_read_b128 v[158:161], v183 offset:41536
	ds_read_b128 v[166:169], v183 offset:36960
	ds_read_b128 v[188:191], v183 offset:41568
	s_nop 0
	s_nop 0
	s_waitcnt lgkmcnt(6)
	v_mfma_f32_32x32x16_bf16 v[80:95], v[68:71], v[98:101], 0
	v_mfma_f32_32x32x16_bf16 v[64:79], v[64:67], v[98:101], 0
	s_waitcnt lgkmcnt(5)
	v_mfma_f32_32x32x16_bf16 v[80:95], v[146:149], v[102:105], v[80:95]
	s_waitcnt lgkmcnt(4)
	v_mfma_f32_32x32x16_bf16 v[64:79], v[150:153], v[102:105], v[64:79]
	s_waitcnt lgkmcnt(3)
	v_mfma_f32_32x32x16_bf16 v[80:95], v[154:157], v[106:109], v[80:95]
	s_waitcnt lgkmcnt(2)
	v_mfma_f32_32x32x16_bf16 v[64:79], v[158:161], v[106:109], v[64:79]
	ds_read_b128 v[158:161], v184 offset:55296
	ds_read_b128 v[154:157], v184 offset:55328
	ds_read_b128 v[150:153], v184 offset:55360
	ds_read_b128 v[146:149], v184 offset:55392
	s_waitcnt lgkmcnt(5)
	v_mfma_f32_32x32x16_bf16 v[80:95], v[166:169], v[110:113], v[80:95]
	s_waitcnt lgkmcnt(4)
	v_mfma_f32_32x32x16_bf16 v[64:79], v[188:191], v[110:113], v[64:79]
	s_nop 11
	v_max3_f32 v96, v64, v65, v66
	v_max3_f32 v96, v96, v67, v68
	v_max3_f32 v96, v96, v69, v70
	v_max3_f32 v96, v96, v71, v72
	v_max3_f32 v96, v96, v73, v74
	v_max3_f32 v96, v96, v75, v76
	v_max3_f32 v96, v96, v77, v78
	v_max3_f32 v96, v96, v79, v80
	v_max3_f32 v96, v96, v81, v82
	v_max3_f32 v96, v96, v83, v84
	v_max3_f32 v96, v96, v85, v86
	v_max3_f32 v96, v96, v87, v88
	v_max3_f32 v96, v96, v89, v90
	v_max3_f32 v96, v96, v91, v92
	v_max3_f32 v96, v96, v93, v94
	v_max_f32_e32 v96, v96, v95
	v_mov_b32_e32 v162, v96
	s_nop 1
	v_permlane32_swap_b32_e32 v96, v162
	v_max3_f32 v186, v187, v96, v162
	v_add_f32_e32 v96, 0x41000000, v187
	v_cmp_gt_f32_e32 vcc, v186, v96
	s_cbranch_vccz .LBB0_287
	v_sub_f32_e32 v96, v187, v186
	v_exp_f32_e32 v96, v96
	s_nop 0
	v_mul_f32_e32 v185, v185, v96
	v_pk_mul_f32 v[62:63], v[62:63], v[96:97] op_sel_hi:[1,0]
	v_pk_mul_f32 v[60:61], v[60:61], v[96:97] op_sel_hi:[1,0]
	v_pk_mul_f32 v[58:59], v[58:59], v[96:97] op_sel_hi:[1,0]
	v_pk_mul_f32 v[56:57], v[56:57], v[96:97] op_sel_hi:[1,0]
	v_pk_mul_f32 v[54:55], v[54:55], v[96:97] op_sel_hi:[1,0]
	v_pk_mul_f32 v[52:53], v[52:53], v[96:97] op_sel_hi:[1,0]
	v_pk_mul_f32 v[50:51], v[50:51], v[96:97] op_sel_hi:[1,0]
	v_pk_mul_f32 v[48:49], v[48:49], v[96:97] op_sel_hi:[1,0]
	v_pk_mul_f32 v[46:47], v[46:47], v[96:97] op_sel_hi:[1,0]
	v_pk_mul_f32 v[44:45], v[44:45], v[96:97] op_sel_hi:[1,0]
	v_pk_mul_f32 v[42:43], v[42:43], v[96:97] op_sel_hi:[1,0]
	v_pk_mul_f32 v[40:41], v[40:41], v[96:97] op_sel_hi:[1,0]
	v_pk_mul_f32 v[38:39], v[38:39], v[96:97] op_sel_hi:[1,0]
	v_pk_mul_f32 v[36:37], v[36:37], v[96:97] op_sel_hi:[1,0]
	v_pk_mul_f32 v[34:35], v[34:35], v[96:97] op_sel_hi:[1,0]
	v_pk_mul_f32 v[32:33], v[32:33], v[96:97] op_sel_hi:[1,0]
	v_pk_mul_f32 v[30:31], v[30:31], v[96:97] op_sel_hi:[1,0]
	v_pk_mul_f32 v[28:29], v[28:29], v[96:97] op_sel_hi:[1,0]
	v_pk_mul_f32 v[26:27], v[26:27], v[96:97] op_sel_hi:[1,0]
	v_pk_mul_f32 v[24:25], v[24:25], v[96:97] op_sel_hi:[1,0]
	v_pk_mul_f32 v[22:23], v[22:23], v[96:97] op_sel_hi:[1,0]
	v_pk_mul_f32 v[20:21], v[20:21], v[96:97] op_sel_hi:[1,0]
	v_pk_mul_f32 v[18:19], v[18:19], v[96:97] op_sel_hi:[1,0]
	v_pk_mul_f32 v[16:17], v[16:17], v[96:97] op_sel_hi:[1,0]
	v_pk_mul_f32 v[14:15], v[14:15], v[96:97] op_sel_hi:[1,0]
	v_pk_mul_f32 v[12:13], v[12:13], v[96:97] op_sel_hi:[1,0]
	v_pk_mul_f32 v[10:11], v[10:11], v[96:97] op_sel_hi:[1,0]
	v_pk_mul_f32 v[8:9], v[8:9], v[96:97] op_sel_hi:[1,0]
	v_pk_mul_f32 v[6:7], v[6:7], v[96:97] op_sel_hi:[1,0]
	v_pk_mul_f32 v[4:5], v[4:5], v[96:97] op_sel_hi:[1,0]
	v_pk_mul_f32 v[2:3], v[2:3], v[96:97] op_sel_hi:[1,0]
	v_pk_mul_f32 v[0:1], v[0:1], v[96:97] op_sel_hi:[1,0]
	s_branch .LBB0_288

.LBB0_288:
	ds_read_b128 v[196:199], v184 offset:59904
	ds_read_b128 v[200:203], v184 offset:59936
	ds_read_b128 v[206:209], v184 offset:59968
	ds_read_b128 v[216:219], v184 offset:60000
	v_sub_f32_e32 v80, v80, v186
	v_sub_f32_e32 v64, v64, v186
	v_sub_f32_e32 v81, v81, v186
	v_sub_f32_e32 v65, v65, v186
	v_sub_f32_e32 v82, v82, v186
	v_sub_f32_e32 v66, v66, v186
	v_sub_f32_e32 v83, v83, v186
	v_sub_f32_e32 v67, v67, v186
	v_sub_f32_e32 v84, v84, v186
	v_sub_f32_e32 v68, v68, v186
	v_sub_f32_e32 v85, v85, v186
	v_sub_f32_e32 v69, v69, v186
	v_sub_f32_e32 v86, v86, v186
	v_sub_f32_e32 v70, v70, v186
	v_sub_f32_e32 v87, v87, v186
	v_sub_f32_e32 v71, v71, v186
	v_sub_f32_e32 v88, v88, v186
	v_sub_f32_e32 v72, v72, v186
	v_sub_f32_e32 v89, v89, v186
	v_sub_f32_e32 v73, v73, v186
	v_sub_f32_e32 v90, v90, v186
	v_sub_f32_e32 v74, v74, v186
	v_sub_f32_e32 v91, v91, v186
	v_sub_f32_e32 v75, v75, v186
	v_sub_f32_e32 v92, v92, v186
	v_sub_f32_e32 v76, v76, v186
	v_sub_f32_e32 v93, v93, v186
	v_sub_f32_e32 v77, v77, v186
	v_sub_f32_e32 v94, v94, v186
	v_sub_f32_e32 v78, v78, v186
	v_sub_f32_e32 v95, v95, v186
	v_sub_f32_e32 v79, v79, v186
	v_exp_f32_e32 v80, v80
	v_exp_f32_e32 v64, v64
	v_exp_f32_e32 v81, v81
	v_exp_f32_e32 v65, v65
	v_exp_f32_e32 v82, v82
	v_exp_f32_e32 v66, v66
	v_exp_f32_e32 v83, v83
	v_exp_f32_e32 v67, v67
	v_exp_f32_e32 v84, v84
	v_exp_f32_e32 v68, v68
	v_exp_f32_e32 v85, v85
	v_exp_f32_e32 v69, v69
	v_exp_f32_e32 v86, v86
	v_exp_f32_e32 v70, v70
	v_exp_f32_e32 v87, v87
	v_exp_f32_e32 v71, v71
	v_exp_f32_e32 v88, v88
	v_exp_f32_e32 v72, v72
	v_exp_f32_e32 v89, v89
	v_exp_f32_e32 v73, v73
	v_exp_f32_e32 v90, v90
	v_exp_f32_e32 v74, v74
	v_exp_f32_e32 v91, v91
	v_exp_f32_e32 v75, v75
	v_exp_f32_e32 v92, v92
	v_exp_f32_e32 v76, v76
	v_exp_f32_e32 v93, v93
	v_exp_f32_e32 v77, v77
	v_exp_f32_e32 v94, v94
	v_exp_f32_e32 v78, v78
	v_exp_f32_e32 v95, v95
	v_exp_f32_e32 v79, v79
	v_cvt_pk_bf16_f32 v166, v80, v81
	v_cvt_pk_bf16_f32 v167, v82, v83
	v_cvt_pk_bf16_f32 v168, v84, v85
	v_cvt_pk_bf16_f32 v169, v86, v87
	v_cvt_pk_bf16_f32 v188, v64, v65
	v_cvt_pk_bf16_f32 v189, v66, v67
	v_cvt_pk_bf16_f32 v190, v68, v69
	v_cvt_pk_bf16_f32 v191, v70, v71
	v_cvt_pk_bf16_f32 v192, v88, v89
	v_cvt_pk_bf16_f32 v193, v90, v91
	v_cvt_pk_bf16_f32 v194, v92, v93
	v_cvt_pk_bf16_f32 v195, v94, v95
	v_cvt_pk_bf16_f32 v220, v72, v73
	v_cvt_pk_bf16_f32 v221, v74, v75
	v_cvt_pk_bf16_f32 v222, v76, v77
	v_cvt_pk_bf16_f32 v223, v78, v79
	s_nop 0
	s_waitcnt lgkmcnt(7)
	v_mfma_f32_32x32x16_bf16 v[48:63], v[158:161], v[166:169], v[48:63]
	s_waitcnt lgkmcnt(6)
	v_mfma_f32_32x32x16_bf16 v[48:63], v[154:157], v[192:195], v[48:63]
	s_waitcnt lgkmcnt(5)
	v_mfma_f32_32x32x16_bf16 v[48:63], v[150:153], v[188:191], v[48:63]
	s_waitcnt lgkmcnt(4)
	v_mfma_f32_32x32x16_bf16 v[48:63], v[146:149], v[220:223], v[48:63]
	s_nop 0
	ds_read_b128 v[146:149], v184 offset:64512
	ds_read_b128 v[150:153], v184 offset:64544
	ds_read_b128 v[154:157], v184 offset:64576
	ds_read_b128 v[158:161], v184 offset:64608
	s_nop 0
	s_waitcnt lgkmcnt(7)
	v_mfma_f32_32x32x16_bf16 v[32:47], v[196:199], v[166:169], v[32:47]
	s_waitcnt lgkmcnt(6)
	v_mfma_f32_32x32x16_bf16 v[32:47], v[200:203], v[192:195], v[32:47]
	s_waitcnt lgkmcnt(5)
	v_mfma_f32_32x32x16_bf16 v[32:47], v[206:209], v[188:191], v[32:47]
	s_waitcnt lgkmcnt(4)
	v_mfma_f32_32x32x16_bf16 v[32:47], v[216:219], v[220:223], v[32:47]
	s_nop 0
	ds_read_b128 v[196:199], v181
	ds_read_b128 v[200:203], v182 offset:32
	ds_read_b128 v[206:209], v182 offset:64
	ds_read_b128 v[216:219], v182 offset:96
	s_nop 0
	s_waitcnt lgkmcnt(7)
	v_mfma_f32_32x32x16_bf16 v[16:31], v[146:149], v[166:169], v[16:31]
	s_waitcnt lgkmcnt(6)
	v_mfma_f32_32x32x16_bf16 v[16:31], v[150:153], v[192:195], v[16:31]
	s_waitcnt lgkmcnt(5)
	v_mfma_f32_32x32x16_bf16 v[16:31], v[154:157], v[188:191], v[16:31]
	s_waitcnt lgkmcnt(4)
	v_mfma_f32_32x32x16_bf16 v[16:31], v[158:161], v[220:223], v[16:31]
	s_nop 0
	s_nop 0
	s_waitcnt lgkmcnt(3)
	v_mfma_f32_32x32x16_bf16 v[0:15], v[196:199], v[166:169], v[0:15]
	s_waitcnt lgkmcnt(2)
	v_mfma_f32_32x32x16_bf16 v[0:15], v[200:203], v[192:195], v[0:15]
	s_waitcnt lgkmcnt(1)
	v_mfma_f32_32x32x16_bf16 v[0:15], v[206:209], v[188:191], v[0:15]
	s_waitcnt lgkmcnt(0)
	v_mfma_f32_32x32x16_bf16 v[0:15], v[216:219], v[220:223], v[0:15]
	s_nop 0
	s_cmp_gt_u32 s37, 37
	s_cselect_b64 s[60:61], -1, 0
	s_and_b64 vcc, exec, s[60:61]
	s_cbranch_vccnz .LBB0_290
	v_mov_b32_e32 v146, v204
	s_nop 0
	v_lshrrev_b32_e32 v96, 3, v146
	v_mul_lo_u32 v147, v96, s55
	v_lshlrev_b32_e32 v96, 4, v146
	v_and_b32_e32 v96, 0x70, v96
	v_add3_u32 v148, 0, v147, v96
	v_add_u32_e32 v96, 0, v96
	v_add_u32_e32 v146, 0x200, v146
	v_add_u32_e32 v147, v96, v147
	v_lshrrev_b32_e32 v146, 3, v146
	s_waitcnt vmcnt(3)
	ds_write_b128 v148, v[130:133]
	s_waitcnt vmcnt(2)
	ds_write_b128 v148, v[134:137] offset:9216
	s_waitcnt vmcnt(1)
	ds_write_b128 v147, v[138:141] offset:18432
	v_mad_u64_u32 v[146:147], s[42:43], v146, s55, v[96:97]
	s_waitcnt vmcnt(0)
	ds_write_b128 v146, v[142:145] offset:18432
